# baseline (speedup 1.0000x reference)
.LBB0_363:
	s_mul_hi_i32 s12, s55, 0x2aaaaaab
	s_lshr_b32 s13, s12, 31
	s_ashr_i32 s12, s12, 4
	s_add_i32 s12, s12, s13
	s_lshl_b32 s14, s55, 8
	s_mul_i32 s13, s12, 0xffffffa0
	s_lshl_b32 s12, s12, 11
	s_and_b32 s14, s14, 0x700
	s_or_b32 s16, s12, s14
	s_add_i32 s13, s13, s55
	s_or_b32 s18, s16, 0x80
	s_lshl_b32 s12, s13, 5
	s_ashr_i32 s19, s18, 31
	s_and_b32 s12, s12, 0xffffff00
	s_lshl_b64 s[14:15], s[18:19], 10
	s_lshl_b64 s[18:19], s[18:19], 11
	s_add_u32 s20, s22, s18
	s_addc_u32 s21, s23, s19
	s_ashr_i32 s13, s12, 31
	s_lshl_b64 s[18:19], s[12:13], 11
	s_add_u32 s56, s24, s18
	s_addc_u32 s57, s25, s19
	s_ashr_i32 s17, s16, 31
	s_barrier
	s_barrier
	s_lshl_b64 s[18:19], s[16:17], 11
	ds_read_b128 v[2:5], v137
	ds_read_b128 v[6:9], v137 offset:1024
	ds_read_b128 v[10:13], v137 offset:2048
	ds_read_b128 v[14:17], v137 offset:3072
	s_add_u32 s17, s22, s18
	s_addc_u32 s58, s23, s19
	s_or_b32 s18, s12, 0x80
	s_ashr_i32 s19, s18, 31
	s_lshl_b64 s[18:19], s[18:19], 11
	s_add_u32 s59, s24, s18
	s_addc_u32 s60, s25, s19
	ds_read_b128 v[18:21], v136 offset:7168
	ds_read_b128 v[22:25], v136 offset:6144
	ds_read_b128 v[26:29], v136 offset:5120
	ds_read_b128 v[30:33], v136 offset:4096
	ds_read_b128 v[34:37], v136 offset:3072
	ds_read_b128 v[38:41], v136 offset:2048
	ds_read_b128 v[42:45], v136 offset:1024
	ds_read_b128 v[46:49], v136
	s_waitcnt lgkmcnt(8)
	s_barrier
	s_waitcnt lgkmcnt(0)
	s_setprio 3
	s_waitcnt lgkmcnt(0)
	v_mfma_f32_16x16x32_bf16 v[50:53], v[46:49], v[2:5], 0
	v_mfma_f32_16x16x32_bf16 v[54:57], v[46:49], v[10:13], 0
	v_mfma_f32_16x16x32_bf16 v[58:61], v[38:41], v[2:5], 0
	v_mfma_f32_16x16x32_bf16 v[62:65], v[38:41], v[10:13], 0
	v_mfma_f32_16x16x32_bf16 v[66:69], v[30:33], v[2:5], 0
	v_mfma_f32_16x16x32_bf16 v[70:73], v[30:33], v[10:13], 0
	v_mfma_f32_16x16x32_bf16 v[74:77], v[22:25], v[2:5], 0
	v_mfma_f32_16x16x32_bf16 v[78:81], v[22:25], v[10:13], 0
	v_mfma_f32_16x16x32_bf16 v[50:53], v[42:45], v[6:9], v[50:53]
	v_mfma_f32_16x16x32_bf16 v[54:57], v[42:45], v[14:17], v[54:57]
	v_mfma_f32_16x16x32_bf16 v[58:61], v[34:37], v[6:9], v[58:61]
	v_mfma_f32_16x16x32_bf16 v[62:65], v[34:37], v[14:17], v[62:65]
	v_mfma_f32_16x16x32_bf16 v[66:69], v[26:29], v[6:9], v[66:69]
	v_mfma_f32_16x16x32_bf16 v[70:73], v[26:29], v[14:17], v[70:73]
	v_mfma_f32_16x16x32_bf16 v[74:77], v[18:21], v[6:9], v[74:77]
	v_mfma_f32_16x16x32_bf16 v[78:81], v[18:21], v[14:17], v[78:81]
	s_setprio 0
	s_barrier
	s_add_u32 s18, s56, 0x100
	s_addc_u32 s19, s57, 0
	s_mov_b32 m0, s28
	ds_read_b128 v[82:85], v137 offset:16384
	ds_read_b128 v[86:89], v137 offset:17408
	ds_read_b128 v[90:93], v137 offset:18432
	ds_read_b128 v[94:97], v137 offset:19456
	s_nop 0
	global_load_lds_dwordx4 v130, s[18:19]
	s_mov_b32 m0, s29
	s_nop 0
	global_load_lds_dwordx4 v132, s[18:19]
	s_barrier
	s_waitcnt lgkmcnt(0)
	s_setprio 3
	s_waitcnt lgkmcnt(0)
	v_mfma_f32_16x16x32_bf16 v[98:101], v[46:49], v[82:85], 0
	v_mfma_f32_16x16x32_bf16 v[46:49], v[46:49], v[90:93], 0
	v_mfma_f32_16x16x32_bf16 v[98:101], v[42:45], v[86:89], v[98:101]
	v_mfma_f32_16x16x32_bf16 v[42:45], v[42:45], v[94:97], v[46:49]
	v_mfma_f32_16x16x32_bf16 v[46:49], v[38:41], v[82:85], 0
	v_mfma_f32_16x16x32_bf16 v[38:41], v[38:41], v[90:93], 0
	v_mfma_f32_16x16x32_bf16 v[46:49], v[34:37], v[86:89], v[46:49]
	v_mfma_f32_16x16x32_bf16 v[34:37], v[34:37], v[94:97], v[38:41]
	v_mfma_f32_16x16x32_bf16 v[38:41], v[30:33], v[82:85], 0
	v_mfma_f32_16x16x32_bf16 v[30:33], v[30:33], v[90:93], 0
	v_mfma_f32_16x16x32_bf16 v[38:41], v[26:29], v[86:89], v[38:41]
	v_mfma_f32_16x16x32_bf16 v[102:105], v[26:29], v[94:97], v[30:33]
	v_mfma_f32_16x16x32_bf16 v[26:29], v[22:25], v[82:85], 0
	v_mfma_f32_16x16x32_bf16 v[22:25], v[22:25], v[90:93], 0
	v_mfma_f32_16x16x32_bf16 v[106:109], v[18:21], v[86:89], v[26:29]
	v_mfma_f32_16x16x32_bf16 v[110:113], v[18:21], v[94:97], v[22:25]
	s_setprio 0
	s_add_u32 s18, s17, 0x100
	s_addc_u32 s19, s58, 0
	s_mov_b32 m0, s27
	s_barrier
	ds_read_b128 v[18:21], v136 offset:16384
	ds_read_b128 v[22:25], v136 offset:17408
	ds_read_b128 v[26:29], v136 offset:18432
	ds_read_b128 v[30:33], v136 offset:19456
	ds_read_b128 v[114:117], v136 offset:20480
	ds_read_b128 v[118:121], v136 offset:21504
	ds_read_b128 v[122:125], v136 offset:22528
	ds_read_b128 v[126:129], v136 offset:23552
	s_nop 0
	global_load_lds_dwordx4 v130, s[18:19]
	s_mov_b32 m0, s30
	s_nop 0
	global_load_lds_dwordx4 v132, s[18:19]
	s_barrier
	s_waitcnt lgkmcnt(0)
	s_setprio 3
	s_waitcnt lgkmcnt(0)
	v_mfma_f32_16x16x32_bf16 v[142:145], v[18:21], v[2:5], 0
	v_mfma_f32_16x16x32_bf16 v[150:153], v[26:29], v[2:5], 0
	v_mfma_f32_16x16x32_bf16 v[158:161], v[114:117], v[2:5], 0
	v_mfma_f32_16x16x32_bf16 v[2:5], v[122:125], v[2:5], 0
	v_mfma_f32_16x16x32_bf16 v[146:149], v[18:21], v[10:13], 0
	v_mfma_f32_16x16x32_bf16 v[154:157], v[26:29], v[10:13], 0
	v_mfma_f32_16x16x32_bf16 v[162:165], v[114:117], v[10:13], 0
	v_mfma_f32_16x16x32_bf16 v[166:169], v[126:129], v[6:9], v[2:5]
	v_mfma_f32_16x16x32_bf16 v[2:5], v[122:125], v[10:13], 0
	v_mfma_f32_16x16x32_bf16 v[142:145], v[22:25], v[6:9], v[142:145]
	v_mfma_f32_16x16x32_bf16 v[146:149], v[22:25], v[14:17], v[146:149]
	v_mfma_f32_16x16x32_bf16 v[150:153], v[30:33], v[6:9], v[150:153]
	v_mfma_f32_16x16x32_bf16 v[154:157], v[30:33], v[14:17], v[154:157]
	v_mfma_f32_16x16x32_bf16 v[158:161], v[118:121], v[6:9], v[158:161]
	v_mfma_f32_16x16x32_bf16 v[162:165], v[118:121], v[14:17], v[162:165]
	v_mfma_f32_16x16x32_bf16 v[170:173], v[126:129], v[14:17], v[2:5]
	s_setprio 0
	s_barrier
	s_add_u32 s18, s59, 0x100
	s_addc_u32 s19, s60, 0
	s_mov_b32 m0, s31
	s_nop 0
	global_load_lds_dwordx4 v130, s[18:19]
	s_mov_b32 m0, s33
	s_nop 0
	global_load_lds_dwordx4 v132, s[18:19]
	s_waitcnt vmcnt(22)
	s_barrier
	s_setprio 3
	v_mfma_f32_16x16x32_bf16 v[2:5], v[18:21], v[82:85], 0
	v_mfma_f32_16x16x32_bf16 v[174:177], v[22:25], v[86:89], v[2:5]
	v_mfma_f32_16x16x32_bf16 v[2:5], v[18:21], v[90:93], 0
	v_mfma_f32_16x16x32_bf16 v[178:181], v[22:25], v[94:97], v[2:5]
	v_mfma_f32_16x16x32_bf16 v[2:5], v[26:29], v[82:85], 0
	v_mfma_f32_16x16x32_bf16 v[182:185], v[30:33], v[86:89], v[2:5]
	v_mfma_f32_16x16x32_bf16 v[2:5], v[26:29], v[90:93], 0
	v_mfma_f32_16x16x32_bf16 v[186:189], v[30:33], v[94:97], v[2:5]
	v_mfma_f32_16x16x32_bf16 v[2:5], v[114:117], v[82:85], 0
	v_mfma_f32_16x16x32_bf16 v[190:193], v[118:121], v[86:89], v[2:5]
	v_mfma_f32_16x16x32_bf16 v[2:5], v[114:117], v[90:93], 0
	v_mfma_f32_16x16x32_bf16 v[194:197], v[118:121], v[94:97], v[2:5]
	v_mfma_f32_16x16x32_bf16 v[2:5], v[122:125], v[82:85], 0
	v_mfma_f32_16x16x32_bf16 v[198:201], v[126:129], v[86:89], v[2:5]
	v_mfma_f32_16x16x32_bf16 v[2:5], v[122:125], v[90:93], 0
	v_mfma_f32_16x16x32_bf16 v[202:205], v[126:129], v[94:97], v[2:5]
	s_setprio 0
	s_barrier
	ds_read_b128 v[114:117], v137 offset:32768
	ds_read_b128 v[118:121], v137 offset:33792
	ds_read_b128 v[122:125], v137 offset:34816
	ds_read_b128 v[126:129], v137 offset:35840
	s_add_u32 s18, s20, 0x100
	s_addc_u32 s19, s21, 0
	s_mov_b32 m0, s34
	ds_read_b128 v[82:85], v136 offset:32768
	ds_read_b128 v[86:89], v136 offset:33792
	ds_read_b128 v[90:93], v136 offset:34816
	ds_read_b128 v[94:97], v136 offset:35840
	ds_read_b128 v[212:215], v136 offset:36864
	ds_read_b128 v[216:219], v136 offset:37888
	ds_read_b128 v[220:223], v136 offset:38912
	ds_read_b128 v[224:227], v136 offset:39936
	s_nop 0
	global_load_lds_dwordx4 v130, s[18:19]
	s_mov_b32 m0, s35
	s_nop 0
	global_load_lds_dwordx4 v132, s[18:19]
	s_waitcnt lgkmcnt(8)
	s_barrier
	s_waitcnt lgkmcnt(0)
	s_setprio 3
	s_waitcnt lgkmcnt(0)
	v_mfma_f32_16x16x32_bf16 v[2:5], v[82:85], v[114:117], v[50:53]
	v_mfma_f32_16x16x32_bf16 v[30:33], v[86:89], v[118:121], v[2:5]
	v_mfma_f32_16x16x32_bf16 v[2:5], v[82:85], v[122:125], v[54:57]
	v_mfma_f32_16x16x32_bf16 v[26:29], v[86:89], v[126:129], v[2:5]
	v_mfma_f32_16x16x32_bf16 v[2:5], v[90:93], v[114:117], v[58:61]
	v_mfma_f32_16x16x32_bf16 v[22:25], v[94:97], v[118:121], v[2:5]
	v_mfma_f32_16x16x32_bf16 v[2:5], v[90:93], v[122:125], v[62:65]
	v_mfma_f32_16x16x32_bf16 v[18:21], v[94:97], v[126:129], v[2:5]
	v_mfma_f32_16x16x32_bf16 v[2:5], v[212:215], v[114:117], v[66:69]
	v_mfma_f32_16x16x32_bf16 v[14:17], v[216:219], v[118:121], v[2:5]
	v_mfma_f32_16x16x32_bf16 v[2:5], v[212:215], v[122:125], v[70:73]
	v_mfma_f32_16x16x32_bf16 v[10:13], v[216:219], v[126:129], v[2:5]
	v_mfma_f32_16x16x32_bf16 v[2:5], v[220:223], v[114:117], v[74:77]
	v_mfma_f32_16x16x32_bf16 v[6:9], v[224:227], v[118:121], v[2:5]
	v_mfma_f32_16x16x32_bf16 v[2:5], v[220:223], v[122:125], v[78:81]
	v_mfma_f32_16x16x32_bf16 v[2:5], v[224:227], v[126:129], v[2:5]
	s_setprio 0
	s_barrier
	s_add_u32 s18, s56, 0x180
	s_addc_u32 s19, s57, 0
	s_mov_b32 m0, s36
	ds_read_b128 v[228:231], v137 offset:49152
	ds_read_b128 v[232:235], v137 offset:50176
	ds_read_b128 v[236:239], v137 offset:51200
	ds_read_b128 v[240:243], v137 offset:52224
	s_nop 0
	global_load_lds_dwordx4 v130, s[18:19]
	s_mov_b32 m0, s37
	s_nop 0
	global_load_lds_dwordx4 v132, s[18:19]
	s_barrier
	s_waitcnt lgkmcnt(0)
	s_setprio 3
	s_waitcnt lgkmcnt(0)
	v_mfma_f32_16x16x32_bf16 v[50:53], v[82:85], v[228:231], v[98:101]
	v_mfma_f32_16x16x32_bf16 v[34:37], v[90:93], v[236:239], v[34:37]
	v_mfma_f32_16x16x32_bf16 v[62:65], v[86:89], v[232:235], v[50:53]
	v_mfma_f32_16x16x32_bf16 v[42:45], v[82:85], v[236:239], v[42:45]
	v_mfma_f32_16x16x32_bf16 v[50:53], v[94:97], v[240:243], v[34:37]
	v_mfma_f32_16x16x32_bf16 v[34:37], v[212:215], v[228:231], v[38:41]
	v_mfma_f32_16x16x32_bf16 v[58:61], v[86:89], v[240:243], v[42:45]
	v_mfma_f32_16x16x32_bf16 v[42:45], v[90:93], v[228:231], v[46:49]
	v_mfma_f32_16x16x32_bf16 v[46:49], v[216:219], v[232:235], v[34:37]
	v_mfma_f32_16x16x32_bf16 v[34:37], v[212:215], v[236:239], v[102:105]
	v_mfma_f32_16x16x32_bf16 v[54:57], v[94:97], v[232:235], v[42:45]
	v_mfma_f32_16x16x32_bf16 v[42:45], v[216:219], v[240:243], v[34:37]
	v_mfma_f32_16x16x32_bf16 v[34:37], v[220:223], v[228:231], v[106:109]
	v_mfma_f32_16x16x32_bf16 v[38:41], v[224:227], v[232:235], v[34:37]
	v_mfma_f32_16x16x32_bf16 v[34:37], v[220:223], v[236:239], v[110:113]
	v_mfma_f32_16x16x32_bf16 v[34:37], v[224:227], v[240:243], v[34:37]
	s_setprio 0
	s_add_u32 s18, s17, 0x180
	s_addc_u32 s19, s58, 0
	s_mov_b32 m0, s38
	s_barrier
	ds_read_b128 v[98:101], v136 offset:49152
	ds_read_b128 v[102:105], v136 offset:50176
	ds_read_b128 v[106:109], v136 offset:51200
	ds_read_b128 v[110:113], v136 offset:52224
	ds_read_b128 v[212:215], v136 offset:53248
	ds_read_b128 v[216:219], v136 offset:54272
	ds_read_b128 v[220:223], v136 offset:55296
	ds_read_b128 v[224:227], v136 offset:56320
	s_nop 0
	global_load_lds_dwordx4 v130, s[18:19]
	s_mov_b32 m0, s39
	s_nop 0
	global_load_lds_dwordx4 v132, s[18:19]
	s_waitcnt vmcnt(10)
	s_barrier
	s_waitcnt lgkmcnt(0)
	s_setprio 3
	s_waitcnt lgkmcnt(0)
	v_mfma_f32_16x16x32_bf16 v[66:69], v[98:101], v[114:117], v[142:145]
	v_mfma_f32_16x16x32_bf16 v[94:97], v[102:105], v[118:121], v[66:69]
	v_mfma_f32_16x16x32_bf16 v[66:69], v[98:101], v[122:125], v[146:149]
	v_mfma_f32_16x16x32_bf16 v[90:93], v[102:105], v[126:129], v[66:69]
	v_mfma_f32_16x16x32_bf16 v[66:69], v[106:109], v[114:117], v[150:153]
	v_mfma_f32_16x16x32_bf16 v[86:89], v[110:113], v[118:121], v[66:69]
	v_mfma_f32_16x16x32_bf16 v[66:69], v[106:109], v[122:125], v[154:157]
	v_mfma_f32_16x16x32_bf16 v[82:85], v[110:113], v[126:129], v[66:69]
	v_mfma_f32_16x16x32_bf16 v[66:69], v[212:215], v[114:117], v[158:161]
	v_mfma_f32_16x16x32_bf16 v[78:81], v[216:219], v[118:121], v[66:69]
	v_mfma_f32_16x16x32_bf16 v[66:69], v[212:215], v[122:125], v[162:165]
	v_mfma_f32_16x16x32_bf16 v[74:77], v[216:219], v[126:129], v[66:69]
	v_mfma_f32_16x16x32_bf16 v[66:69], v[220:223], v[114:117], v[166:169]
	v_mfma_f32_16x16x32_bf16 v[70:73], v[224:227], v[118:121], v[66:69]
	v_mfma_f32_16x16x32_bf16 v[66:69], v[220:223], v[122:125], v[170:173]
	v_mfma_f32_16x16x32_bf16 v[66:69], v[224:227], v[126:129], v[66:69]
	s_setprio 0
	s_barrier
	s_add_u32 s18, s59, 0x180
	s_addc_u32 s19, s60, 0
	s_mov_b32 m0, s40
	s_nop 0
	global_load_lds_dwordx4 v130, s[18:19]
	s_mov_b32 m0, s41
	s_nop 0
	global_load_lds_dwordx4 v132, s[18:19]
	ds_read_b128 v[138:141], v137
	ds_read_b128 v[142:145], v137 offset:1024
	ds_read_b128 v[146:149], v137 offset:2048
	ds_read_b128 v[150:153], v137 offset:3072
	s_waitcnt vmcnt(6)
	s_barrier
	s_setprio 3
	v_mfma_f32_16x16x32_bf16 v[114:117], v[98:101], v[228:231], v[174:177]
	v_mfma_f32_16x16x32_bf16 v[98:101], v[98:101], v[236:239], v[178:181]
	v_mfma_f32_16x16x32_bf16 v[122:125], v[102:105], v[240:243], v[98:101]
	v_mfma_f32_16x16x32_bf16 v[98:101], v[106:109], v[228:231], v[182:185]
	v_mfma_f32_16x16x32_bf16 v[118:121], v[110:113], v[232:235], v[98:101]
	v_mfma_f32_16x16x32_bf16 v[98:101], v[106:109], v[236:239], v[186:189]
	v_mfma_f32_16x16x32_bf16 v[126:129], v[102:105], v[232:235], v[114:117]
	v_mfma_f32_16x16x32_bf16 v[114:117], v[110:113], v[240:243], v[98:101]
	v_mfma_f32_16x16x32_bf16 v[98:101], v[212:215], v[228:231], v[190:193]
	v_mfma_f32_16x16x32_bf16 v[110:113], v[216:219], v[232:235], v[98:101]
	v_mfma_f32_16x16x32_bf16 v[98:101], v[212:215], v[236:239], v[194:197]
	v_mfma_f32_16x16x32_bf16 v[106:109], v[216:219], v[240:243], v[98:101]
	v_mfma_f32_16x16x32_bf16 v[98:101], v[220:223], v[228:231], v[198:201]
	v_mfma_f32_16x16x32_bf16 v[102:105], v[224:227], v[232:235], v[98:101]
	v_mfma_f32_16x16x32_bf16 v[98:101], v[220:223], v[236:239], v[202:205]
	v_mfma_f32_16x16x32_bf16 v[98:101], v[224:227], v[240:243], v[98:101]
	s_setprio 0
	s_mov_b32 s61, 0
	s_mov_b64 s[18:19], 0
	s_barrier
.LBB0_364:
	s_add_u32 s64, s20, s18
	s_addc_u32 s65, s21, s19
	s_add_u32 s62, s64, 0x180
	s_addc_u32 s63, s65, 0
	s_mov_b32 m0, s42
	ds_read_b128 v[154:157], v136
	ds_read_b128 v[158:161], v136 offset:1024
	ds_read_b128 v[162:165], v136 offset:2048
	ds_read_b128 v[166:169], v136 offset:3072
	ds_read_b128 v[170:173], v136 offset:4096
	ds_read_b128 v[174:177], v136 offset:5120
	ds_read_b128 v[178:181], v136 offset:6144
	ds_read_b128 v[182:185], v136 offset:7168
	s_nop 0
	global_load_lds_dwordx4 v130, s[62:63]
	s_mov_b32 m0, s43
	s_nop 0
	global_load_lds_dwordx4 v132, s[62:63]
	s_waitcnt lgkmcnt(8)
	s_barrier
	s_waitcnt lgkmcnt(0)
	s_setprio 3
	s_waitcnt lgkmcnt(0)
	v_mfma_f32_16x16x32_bf16 v[30:33], v[154:157], v[138:141], v[30:33]
	v_mfma_f32_16x16x32_bf16 v[26:29], v[154:157], v[146:149], v[26:29]
	v_mfma_f32_16x16x32_bf16 v[22:25], v[162:165], v[138:141], v[22:25]
	v_mfma_f32_16x16x32_bf16 v[18:21], v[162:165], v[146:149], v[18:21]
	v_mfma_f32_16x16x32_bf16 v[14:17], v[170:173], v[138:141], v[14:17]
	v_mfma_f32_16x16x32_bf16 v[10:13], v[170:173], v[146:149], v[10:13]
	v_mfma_f32_16x16x32_bf16 v[6:9], v[178:181], v[138:141], v[6:9]
	v_mfma_f32_16x16x32_bf16 v[2:5], v[178:181], v[146:149], v[2:5]
	v_mfma_f32_16x16x32_bf16 v[30:33], v[158:161], v[142:145], v[30:33]
	v_mfma_f32_16x16x32_bf16 v[26:29], v[158:161], v[150:153], v[26:29]
	v_mfma_f32_16x16x32_bf16 v[22:25], v[166:169], v[142:145], v[22:25]
	v_mfma_f32_16x16x32_bf16 v[18:21], v[166:169], v[150:153], v[18:21]
	v_mfma_f32_16x16x32_bf16 v[14:17], v[174:177], v[142:145], v[14:17]
	v_mfma_f32_16x16x32_bf16 v[10:13], v[174:177], v[150:153], v[10:13]
	v_mfma_f32_16x16x32_bf16 v[6:9], v[182:185], v[142:145], v[6:9]
	v_mfma_f32_16x16x32_bf16 v[2:5], v[182:185], v[150:153], v[2:5]
	s_setprio 0
	s_barrier
	s_add_u32 s66, s56, s18
	s_addc_u32 s67, s57, s19
	s_add_u32 s62, s66, 0x200
	s_addc_u32 s63, s67, 0
	s_mov_b32 m0, s28
	ds_read_b128 v[186:189], v137 offset:16384
	ds_read_b128 v[190:193], v137 offset:17408
	ds_read_b128 v[194:197], v137 offset:18432
	ds_read_b128 v[198:201], v137 offset:19456
	s_nop 0
	global_load_lds_dwordx4 v130, s[62:63]
	s_mov_b32 m0, s29
	s_nop 0
	global_load_lds_dwordx4 v132, s[62:63]
	s_barrier
	s_waitcnt lgkmcnt(0)
	s_setprio 3
	s_waitcnt lgkmcnt(0)
	v_mfma_f32_16x16x32_bf16 v[62:65], v[154:157], v[186:189], v[62:65]
	v_mfma_f32_16x16x32_bf16 v[58:61], v[154:157], v[194:197], v[58:61]
	v_mfma_f32_16x16x32_bf16 v[54:57], v[162:165], v[186:189], v[54:57]
	v_mfma_f32_16x16x32_bf16 v[50:53], v[162:165], v[194:197], v[50:53]
	v_mfma_f32_16x16x32_bf16 v[46:49], v[170:173], v[186:189], v[46:49]
	v_mfma_f32_16x16x32_bf16 v[42:45], v[170:173], v[194:197], v[42:45]
	v_mfma_f32_16x16x32_bf16 v[38:41], v[178:181], v[186:189], v[38:41]
	v_mfma_f32_16x16x32_bf16 v[34:37], v[178:181], v[194:197], v[34:37]
	v_mfma_f32_16x16x32_bf16 v[62:65], v[158:161], v[190:193], v[62:65]
	v_mfma_f32_16x16x32_bf16 v[58:61], v[158:161], v[198:201], v[58:61]
	v_mfma_f32_16x16x32_bf16 v[54:57], v[166:169], v[190:193], v[54:57]
	v_mfma_f32_16x16x32_bf16 v[50:53], v[166:169], v[198:201], v[50:53]
	v_mfma_f32_16x16x32_bf16 v[46:49], v[174:177], v[190:193], v[46:49]
	v_mfma_f32_16x16x32_bf16 v[42:45], v[174:177], v[198:201], v[42:45]
	v_mfma_f32_16x16x32_bf16 v[38:41], v[182:185], v[190:193], v[38:41]
	v_mfma_f32_16x16x32_bf16 v[34:37], v[182:185], v[198:201], v[34:37]
	s_setprio 0
	s_add_u32 s68, s17, s18
	s_addc_u32 s69, s58, s19
	s_add_u32 s62, s68, 0x200
	s_addc_u32 s63, s69, 0
	s_mov_b32 m0, s27
	s_barrier
	ds_read_b128 v[154:157], v136 offset:16384
	ds_read_b128 v[158:161], v136 offset:17408
	ds_read_b128 v[162:165], v136 offset:18432
	ds_read_b128 v[166:169], v136 offset:19456
	ds_read_b128 v[170:173], v136 offset:20480
	ds_read_b128 v[174:177], v136 offset:21504
	ds_read_b128 v[178:181], v136 offset:22528
	ds_read_b128 v[182:185], v136 offset:23552
	s_nop 0
	global_load_lds_dwordx4 v130, s[62:63]
	s_mov_b32 m0, s30
	s_nop 0
	global_load_lds_dwordx4 v132, s[62:63]
	s_waitcnt vmcnt(10)
	s_barrier
	s_waitcnt lgkmcnt(0)
	s_setprio 3
	s_waitcnt lgkmcnt(0)
	v_mfma_f32_16x16x32_bf16 v[94:97], v[154:157], v[138:141], v[94:97]
	v_mfma_f32_16x16x32_bf16 v[90:93], v[154:157], v[146:149], v[90:93]
	v_mfma_f32_16x16x32_bf16 v[86:89], v[162:165], v[138:141], v[86:89]
	v_mfma_f32_16x16x32_bf16 v[82:85], v[162:165], v[146:149], v[82:85]
	v_mfma_f32_16x16x32_bf16 v[78:81], v[170:173], v[138:141], v[78:81]
	v_mfma_f32_16x16x32_bf16 v[74:77], v[170:173], v[146:149], v[74:77]
	v_mfma_f32_16x16x32_bf16 v[70:73], v[178:181], v[138:141], v[70:73]
	v_mfma_f32_16x16x32_bf16 v[66:69], v[178:181], v[146:149], v[66:69]
	v_mfma_f32_16x16x32_bf16 v[94:97], v[158:161], v[142:145], v[94:97]
	v_mfma_f32_16x16x32_bf16 v[90:93], v[158:161], v[150:153], v[90:93]
	v_mfma_f32_16x16x32_bf16 v[86:89], v[166:169], v[142:145], v[86:89]
	v_mfma_f32_16x16x32_bf16 v[82:85], v[166:169], v[150:153], v[82:85]
	v_mfma_f32_16x16x32_bf16 v[78:81], v[174:177], v[142:145], v[78:81]
	v_mfma_f32_16x16x32_bf16 v[74:77], v[174:177], v[150:153], v[74:77]
	v_mfma_f32_16x16x32_bf16 v[70:73], v[182:185], v[142:145], v[70:73]
	v_mfma_f32_16x16x32_bf16 v[66:69], v[182:185], v[150:153], v[66:69]
	s_setprio 0
	s_barrier
	s_add_u32 s70, s59, s18
	s_addc_u32 s71, s60, s19
	s_add_u32 s62, s70, 0x200
	s_addc_u32 s63, s71, 0
	s_mov_b32 m0, s31
	s_nop 0
	global_load_lds_dwordx4 v130, s[62:63]
	s_mov_b32 m0, s33
	s_nop 0
	global_load_lds_dwordx4 v132, s[62:63]
	ds_read_b128 v[138:141], v137 offset:32768
	ds_read_b128 v[142:145], v137 offset:33792
	ds_read_b128 v[146:149], v137 offset:34816
	ds_read_b128 v[150:153], v137 offset:35840
	s_waitcnt vmcnt(6)
	s_barrier
	s_setprio 3
	v_mfma_f32_16x16x32_bf16 v[126:129], v[154:157], v[186:189], v[126:129]
	v_mfma_f32_16x16x32_bf16 v[122:125], v[154:157], v[194:197], v[122:125]
	v_mfma_f32_16x16x32_bf16 v[118:121], v[162:165], v[186:189], v[118:121]
	v_mfma_f32_16x16x32_bf16 v[114:117], v[162:165], v[194:197], v[114:117]
	v_mfma_f32_16x16x32_bf16 v[110:113], v[170:173], v[186:189], v[110:113]
	v_mfma_f32_16x16x32_bf16 v[106:109], v[170:173], v[194:197], v[106:109]
	v_mfma_f32_16x16x32_bf16 v[102:105], v[178:181], v[186:189], v[102:105]
	v_mfma_f32_16x16x32_bf16 v[98:101], v[178:181], v[194:197], v[98:101]
	v_mfma_f32_16x16x32_bf16 v[126:129], v[158:161], v[190:193], v[126:129]
	v_mfma_f32_16x16x32_bf16 v[122:125], v[158:161], v[198:201], v[122:125]
	v_mfma_f32_16x16x32_bf16 v[118:121], v[166:169], v[190:193], v[118:121]
	v_mfma_f32_16x16x32_bf16 v[114:117], v[166:169], v[198:201], v[114:117]
	v_mfma_f32_16x16x32_bf16 v[110:113], v[174:177], v[190:193], v[110:113]
	v_mfma_f32_16x16x32_bf16 v[106:109], v[174:177], v[198:201], v[106:109]
	v_mfma_f32_16x16x32_bf16 v[102:105], v[182:185], v[190:193], v[102:105]
	v_mfma_f32_16x16x32_bf16 v[98:101], v[182:185], v[198:201], v[98:101]
	s_setprio 0
	s_barrier
	s_add_u32 s62, s64, 0x200
	s_addc_u32 s63, s65, 0
	s_mov_b32 m0, s34
	ds_read_b128 v[154:157], v136 offset:32768
	ds_read_b128 v[158:161], v136 offset:33792
	ds_read_b128 v[162:165], v136 offset:34816
	ds_read_b128 v[166:169], v136 offset:35840
	ds_read_b128 v[170:173], v136 offset:36864
	ds_read_b128 v[174:177], v136 offset:37888
	ds_read_b128 v[178:181], v136 offset:38912
	ds_read_b128 v[182:185], v136 offset:39936
	s_nop 0
	global_load_lds_dwordx4 v130, s[62:63]
	s_mov_b32 m0, s35
	s_nop 0
	global_load_lds_dwordx4 v132, s[62:63]
	s_waitcnt lgkmcnt(8)
	s_barrier
	s_waitcnt lgkmcnt(0)
	s_setprio 3
	s_waitcnt lgkmcnt(0)
	v_mfma_f32_16x16x32_bf16 v[30:33], v[154:157], v[138:141], v[30:33]
	v_mfma_f32_16x16x32_bf16 v[26:29], v[154:157], v[146:149], v[26:29]
	v_mfma_f32_16x16x32_bf16 v[22:25], v[162:165], v[138:141], v[22:25]
	v_mfma_f32_16x16x32_bf16 v[18:21], v[162:165], v[146:149], v[18:21]
	v_mfma_f32_16x16x32_bf16 v[14:17], v[170:173], v[138:141], v[14:17]
	v_mfma_f32_16x16x32_bf16 v[10:13], v[170:173], v[146:149], v[10:13]
	v_mfma_f32_16x16x32_bf16 v[6:9], v[178:181], v[138:141], v[6:9]
	v_mfma_f32_16x16x32_bf16 v[2:5], v[178:181], v[146:149], v[2:5]
	v_mfma_f32_16x16x32_bf16 v[30:33], v[158:161], v[142:145], v[30:33]
	v_mfma_f32_16x16x32_bf16 v[26:29], v[158:161], v[150:153], v[26:29]
	v_mfma_f32_16x16x32_bf16 v[22:25], v[166:169], v[142:145], v[22:25]
	v_mfma_f32_16x16x32_bf16 v[18:21], v[166:169], v[150:153], v[18:21]
	v_mfma_f32_16x16x32_bf16 v[14:17], v[174:177], v[142:145], v[14:17]
	v_mfma_f32_16x16x32_bf16 v[10:13], v[174:177], v[150:153], v[10:13]
	v_mfma_f32_16x16x32_bf16 v[6:9], v[182:185], v[142:145], v[6:9]
	v_mfma_f32_16x16x32_bf16 v[2:5], v[182:185], v[150:153], v[2:5]
	s_setprio 0
	s_barrier
	s_add_u32 s62, s66, 0x280
	s_addc_u32 s63, s67, 0
	s_mov_b32 m0, s36
	ds_read_b128 v[186:189], v137 offset:49152
	ds_read_b128 v[190:193], v137 offset:50176
	ds_read_b128 v[194:197], v137 offset:51200
	ds_read_b128 v[198:201], v137 offset:52224
	s_nop 0
	global_load_lds_dwordx4 v130, s[62:63]
	s_mov_b32 m0, s37
	s_nop 0
	global_load_lds_dwordx4 v132, s[62:63]
	s_barrier
	s_waitcnt lgkmcnt(0)
	s_setprio 3
	s_waitcnt lgkmcnt(0)
	v_mfma_f32_16x16x32_bf16 v[62:65], v[154:157], v[186:189], v[62:65]
	v_mfma_f32_16x16x32_bf16 v[58:61], v[154:157], v[194:197], v[58:61]
	v_mfma_f32_16x16x32_bf16 v[54:57], v[162:165], v[186:189], v[54:57]
	v_mfma_f32_16x16x32_bf16 v[50:53], v[162:165], v[194:197], v[50:53]
	v_mfma_f32_16x16x32_bf16 v[46:49], v[170:173], v[186:189], v[46:49]
	v_mfma_f32_16x16x32_bf16 v[42:45], v[170:173], v[194:197], v[42:45]
	v_mfma_f32_16x16x32_bf16 v[38:41], v[178:181], v[186:189], v[38:41]
	v_mfma_f32_16x16x32_bf16 v[34:37], v[178:181], v[194:197], v[34:37]
	v_mfma_f32_16x16x32_bf16 v[62:65], v[158:161], v[190:193], v[62:65]
	v_mfma_f32_16x16x32_bf16 v[58:61], v[158:161], v[198:201], v[58:61]
	v_mfma_f32_16x16x32_bf16 v[54:57], v[166:169], v[190:193], v[54:57]
	v_mfma_f32_16x16x32_bf16 v[50:53], v[166:169], v[198:201], v[50:53]
	v_mfma_f32_16x16x32_bf16 v[46:49], v[174:177], v[190:193], v[46:49]
	v_mfma_f32_16x16x32_bf16 v[42:45], v[174:177], v[198:201], v[42:45]
	v_mfma_f32_16x16x32_bf16 v[38:41], v[182:185], v[190:193], v[38:41]
	v_mfma_f32_16x16x32_bf16 v[34:37], v[182:185], v[198:201], v[34:37]
	s_setprio 0
	s_add_u32 s62, s68, 0x280
	s_addc_u32 s63, s69, 0
	s_mov_b32 m0, s38
	s_barrier
	ds_read_b128 v[154:157], v136 offset:49152
	ds_read_b128 v[158:161], v136 offset:50176
	ds_read_b128 v[162:165], v136 offset:51200
	ds_read_b128 v[166:169], v136 offset:52224
	ds_read_b128 v[170:173], v136 offset:53248
	ds_read_b128 v[174:177], v136 offset:54272
	ds_read_b128 v[178:181], v136 offset:55296
	ds_read_b128 v[182:185], v136 offset:56320
	s_nop 0
	global_load_lds_dwordx4 v130, s[62:63]
	s_mov_b32 m0, s39
	s_nop 0
	global_load_lds_dwordx4 v132, s[62:63]
	s_waitcnt vmcnt(10)
	s_barrier
	s_waitcnt lgkmcnt(0)
	s_setprio 3
	s_waitcnt lgkmcnt(0)
	v_mfma_f32_16x16x32_bf16 v[94:97], v[154:157], v[138:141], v[94:97]
	v_mfma_f32_16x16x32_bf16 v[90:93], v[154:157], v[146:149], v[90:93]
	v_mfma_f32_16x16x32_bf16 v[86:89], v[162:165], v[138:141], v[86:89]
	v_mfma_f32_16x16x32_bf16 v[82:85], v[162:165], v[146:149], v[82:85]
	v_mfma_f32_16x16x32_bf16 v[78:81], v[170:173], v[138:141], v[78:81]
	v_mfma_f32_16x16x32_bf16 v[74:77], v[170:173], v[146:149], v[74:77]
	v_mfma_f32_16x16x32_bf16 v[70:73], v[178:181], v[138:141], v[70:73]
	v_mfma_f32_16x16x32_bf16 v[66:69], v[178:181], v[146:149], v[66:69]
	v_mfma_f32_16x16x32_bf16 v[94:97], v[158:161], v[142:145], v[94:97]
	v_mfma_f32_16x16x32_bf16 v[90:93], v[158:161], v[150:153], v[90:93]
	v_mfma_f32_16x16x32_bf16 v[86:89], v[166:169], v[142:145], v[86:89]
	v_mfma_f32_16x16x32_bf16 v[82:85], v[166:169], v[150:153], v[82:85]
	v_mfma_f32_16x16x32_bf16 v[78:81], v[174:177], v[142:145], v[78:81]
	v_mfma_f32_16x16x32_bf16 v[74:77], v[174:177], v[150:153], v[74:77]
	v_mfma_f32_16x16x32_bf16 v[70:73], v[182:185], v[142:145], v[70:73]
	v_mfma_f32_16x16x32_bf16 v[66:69], v[182:185], v[150:153], v[66:69]
	s_setprio 0
	s_barrier
	s_add_u32 s62, s70, 0x280
	s_addc_u32 s63, s71, 0
	s_mov_b32 m0, s40
	s_nop 0
	global_load_lds_dwordx4 v130, s[62:63]
	s_mov_b32 m0, s41
	s_nop 0
	global_load_lds_dwordx4 v132, s[62:63]
	ds_read_b128 v[138:141], v137
	ds_read_b128 v[142:145], v137 offset:1024
	ds_read_b128 v[146:149], v137 offset:2048
	ds_read_b128 v[150:153], v137 offset:3072
	s_waitcnt vmcnt(6)
	s_barrier
	s_setprio 3
	v_mfma_f32_16x16x32_bf16 v[126:129], v[154:157], v[186:189], v[126:129]
	v_mfma_f32_16x16x32_bf16 v[122:125], v[154:157], v[194:197], v[122:125]
	v_mfma_f32_16x16x32_bf16 v[118:121], v[162:165], v[186:189], v[118:121]
	v_mfma_f32_16x16x32_bf16 v[114:117], v[162:165], v[194:197], v[114:117]
	v_mfma_f32_16x16x32_bf16 v[110:113], v[170:173], v[186:189], v[110:113]
	v_mfma_f32_16x16x32_bf16 v[106:109], v[170:173], v[194:197], v[106:109]
	v_mfma_f32_16x16x32_bf16 v[102:105], v[178:181], v[186:189], v[102:105]
	v_mfma_f32_16x16x32_bf16 v[98:101], v[178:181], v[194:197], v[98:101]
	v_mfma_f32_16x16x32_bf16 v[126:129], v[158:161], v[190:193], v[126:129]
	v_mfma_f32_16x16x32_bf16 v[122:125], v[158:161], v[198:201], v[122:125]
	v_mfma_f32_16x16x32_bf16 v[118:121], v[166:169], v[190:193], v[118:121]
	v_mfma_f32_16x16x32_bf16 v[114:117], v[166:169], v[198:201], v[114:117]
	v_mfma_f32_16x16x32_bf16 v[110:113], v[174:177], v[190:193], v[110:113]
	v_mfma_f32_16x16x32_bf16 v[106:109], v[174:177], v[198:201], v[106:109]
	v_mfma_f32_16x16x32_bf16 v[102:105], v[182:185], v[190:193], v[102:105]
	v_mfma_f32_16x16x32_bf16 v[98:101], v[182:185], v[198:201], v[98:101]
	s_setprio 0
	s_add_i32 s61, s61, 2
	s_add_u32 s18, s18, 0x100
	s_addc_u32 s19, s19, 0
	s_cmp_gt_u32 s61, 11
	s_barrier
	s_cbranch_scc0 .LBB0_364
	s_lshl_b64 s[14:15], s[14:15], 1
	s_add_u32 s14, s44, s14
	s_addc_u32 s15, s45, s15
	s_mov_b32 m0, s42
	ds_read_b128 v[142:145], v137
	ds_read_b128 v[146:149], v137 offset:1024
	ds_read_b128 v[150:153], v137 offset:2048
	ds_read_b128 v[154:157], v137 offset:3072
	ds_read_b128 v[158:161], v136
	ds_read_b128 v[162:165], v136 offset:1024
	ds_read_b128 v[166:169], v136 offset:2048
	ds_read_b128 v[170:173], v136 offset:3072
	ds_read_b128 v[174:177], v136 offset:4096
	ds_read_b128 v[178:181], v136 offset:5120
	ds_read_b128 v[182:185], v136 offset:6144
	ds_read_b128 v[186:189], v136 offset:7168
	s_nop 0
	global_load_lds_dwordx4 v130, s[14:15]
	s_mov_b32 m0, s43
	s_nop 0
	global_load_lds_dwordx4 v132, s[14:15]
	s_barrier
	s_waitcnt lgkmcnt(0)
	s_setprio 3
	s_waitcnt lgkmcnt(0)
	v_mfma_f32_16x16x32_bf16 v[30:33], v[158:161], v[142:145], v[30:33]
	v_mfma_f32_16x16x32_bf16 v[26:29], v[158:161], v[150:153], v[26:29]
	v_mfma_f32_16x16x32_bf16 v[22:25], v[166:169], v[142:145], v[22:25]
	v_mfma_f32_16x16x32_bf16 v[18:21], v[166:169], v[150:153], v[18:21]
	v_mfma_f32_16x16x32_bf16 v[14:17], v[174:177], v[142:145], v[14:17]
	v_mfma_f32_16x16x32_bf16 v[10:13], v[174:177], v[150:153], v[10:13]
	v_mfma_f32_16x16x32_bf16 v[6:9], v[182:185], v[142:145], v[6:9]
	v_mfma_f32_16x16x32_bf16 v[2:5], v[182:185], v[150:153], v[2:5]
	v_mfma_f32_16x16x32_bf16 v[30:33], v[162:165], v[146:149], v[30:33]
	v_mfma_f32_16x16x32_bf16 v[26:29], v[162:165], v[154:157], v[26:29]
	v_mfma_f32_16x16x32_bf16 v[22:25], v[170:173], v[146:149], v[22:25]
	v_mfma_f32_16x16x32_bf16 v[18:21], v[170:173], v[154:157], v[18:21]
	v_mfma_f32_16x16x32_bf16 v[14:17], v[178:181], v[146:149], v[14:17]
	v_mfma_f32_16x16x32_bf16 v[10:13], v[178:181], v[154:157], v[10:13]
	v_mfma_f32_16x16x32_bf16 v[6:9], v[186:189], v[146:149], v[6:9]
	v_mfma_f32_16x16x32_bf16 v[2:5], v[186:189], v[154:157], v[2:5]
	s_setprio 0
	s_barrier
	ds_read_b128 v[190:193], v137 offset:16384
	ds_read_b128 v[194:197], v137 offset:17408
	ds_read_b128 v[198:201], v137 offset:18432
	ds_read_b128 v[202:205], v137 offset:19456
	s_barrier
	s_waitcnt lgkmcnt(0)
	s_setprio 3
	s_waitcnt lgkmcnt(0)
	v_mfma_f32_16x16x32_bf16 v[62:65], v[158:161], v[190:193], v[62:65]
	v_mfma_f32_16x16x32_bf16 v[58:61], v[158:161], v[198:201], v[58:61]
	v_mfma_f32_16x16x32_bf16 v[54:57], v[166:169], v[190:193], v[54:57]
	v_mfma_f32_16x16x32_bf16 v[50:53], v[166:169], v[198:201], v[50:53]
	v_mfma_f32_16x16x32_bf16 v[46:49], v[174:177], v[190:193], v[46:49]
	v_mfma_f32_16x16x32_bf16 v[42:45], v[174:177], v[198:201], v[42:45]
	v_mfma_f32_16x16x32_bf16 v[38:41], v[182:185], v[190:193], v[38:41]
	v_mfma_f32_16x16x32_bf16 v[34:37], v[182:185], v[198:201], v[34:37]
	v_mfma_f32_16x16x32_bf16 v[62:65], v[162:165], v[194:197], v[62:65]
	v_mfma_f32_16x16x32_bf16 v[58:61], v[162:165], v[202:205], v[58:61]
	v_mfma_f32_16x16x32_bf16 v[54:57], v[170:173], v[194:197], v[54:57]
	v_mfma_f32_16x16x32_bf16 v[50:53], v[170:173], v[202:205], v[50:53]
	v_mfma_f32_16x16x32_bf16 v[46:49], v[178:181], v[194:197], v[46:49]
	v_mfma_f32_16x16x32_bf16 v[42:45], v[178:181], v[202:205], v[42:45]
	v_mfma_f32_16x16x32_bf16 v[38:41], v[186:189], v[194:197], v[38:41]
	v_mfma_f32_16x16x32_bf16 v[34:37], v[186:189], v[202:205], v[34:37]
	s_setprio 0
	s_barrier
	ds_read_b128 v[158:161], v136 offset:16384
	ds_read_b128 v[162:165], v136 offset:17408
	ds_read_b128 v[166:169], v136 offset:18432
	ds_read_b128 v[170:173], v136 offset:19456
	ds_read_b128 v[174:177], v136 offset:20480
	ds_read_b128 v[178:181], v136 offset:21504
	ds_read_b128 v[182:185], v136 offset:22528
	ds_read_b128 v[186:189], v136 offset:23552
	s_waitcnt vmcnt(4)
	s_barrier
	s_waitcnt lgkmcnt(0)
	s_setprio 3
	s_waitcnt lgkmcnt(0)
	v_mfma_f32_16x16x32_bf16 v[94:97], v[158:161], v[142:145], v[94:97]
	v_mfma_f32_16x16x32_bf16 v[90:93], v[158:161], v[150:153], v[90:93]
	v_mfma_f32_16x16x32_bf16 v[86:89], v[166:169], v[142:145], v[86:89]
	v_mfma_f32_16x16x32_bf16 v[82:85], v[166:169], v[150:153], v[82:85]
	v_mfma_f32_16x16x32_bf16 v[78:81], v[174:177], v[142:145], v[78:81]
	v_mfma_f32_16x16x32_bf16 v[74:77], v[174:177], v[150:153], v[74:77]
	v_mfma_f32_16x16x32_bf16 v[70:73], v[182:185], v[142:145], v[70:73]
	v_mfma_f32_16x16x32_bf16 v[66:69], v[182:185], v[150:153], v[66:69]
	v_mfma_f32_16x16x32_bf16 v[212:215], v[162:165], v[146:149], v[94:97]
	v_mfma_f32_16x16x32_bf16 v[216:219], v[162:165], v[154:157], v[90:93]
	v_mfma_f32_16x16x32_bf16 v[220:223], v[170:173], v[146:149], v[86:89]
	v_mfma_f32_16x16x32_bf16 v[224:227], v[170:173], v[154:157], v[82:85]
	v_mfma_f32_16x16x32_bf16 v[228:231], v[178:181], v[146:149], v[78:81]
	v_mfma_f32_16x16x32_bf16 v[232:235], v[178:181], v[154:157], v[74:77]
	v_mfma_f32_16x16x32_bf16 v[142:145], v[186:189], v[146:149], v[70:73]
	v_mfma_f32_16x16x32_bf16 v[146:149], v[186:189], v[154:157], v[66:69]
	s_setprio 0
	s_setprio 3
	v_mfma_f32_16x16x32_bf16 v[66:69], v[158:161], v[190:193], v[126:129]
	v_mfma_f32_16x16x32_bf16 v[150:153], v[162:165], v[194:197], v[66:69]
	v_mfma_f32_16x16x32_bf16 v[66:69], v[158:161], v[198:201], v[122:125]
	v_mfma_f32_16x16x32_bf16 v[154:157], v[162:165], v[202:205], v[66:69]
	v_mfma_f32_16x16x32_bf16 v[66:69], v[166:169], v[190:193], v[118:121]
	v_mfma_f32_16x16x32_bf16 v[158:161], v[170:173], v[194:197], v[66:69]
	v_mfma_f32_16x16x32_bf16 v[66:69], v[166:169], v[198:201], v[114:117]
	v_mfma_f32_16x16x32_bf16 v[162:165], v[170:173], v[202:205], v[66:69]
	v_mfma_f32_16x16x32_bf16 v[66:69], v[174:177], v[190:193], v[110:113]
	v_mfma_f32_16x16x32_bf16 v[166:169], v[178:181], v[194:197], v[66:69]
	v_mfma_f32_16x16x32_bf16 v[66:69], v[174:177], v[198:201], v[106:109]
	v_mfma_f32_16x16x32_bf16 v[170:173], v[178:181], v[202:205], v[66:69]
	v_mfma_f32_16x16x32_bf16 v[66:69], v[182:185], v[190:193], v[102:105]
	v_mfma_f32_16x16x32_bf16 v[174:177], v[186:189], v[194:197], v[66:69]
	v_mfma_f32_16x16x32_bf16 v[66:69], v[182:185], v[198:201], v[98:101]
	v_mfma_f32_16x16x32_bf16 v[178:181], v[186:189], v[202:205], v[66:69]
	s_setprio 0
	s_barrier
	ds_read_b128 v[182:185], v137 offset:32768
	ds_read_b128 v[186:189], v137 offset:33792
	ds_read_b128 v[190:193], v137 offset:34816
	ds_read_b128 v[194:197], v137 offset:35840
	s_nop 0
	ds_read_b128 v[66:69], v136 offset:32768
	ds_read_b128 v[70:73], v136 offset:33792
	ds_read_b128 v[82:85], v136 offset:34816
	ds_read_b128 v[86:89], v136 offset:35840
	ds_read_b128 v[198:201], v136 offset:36864
	ds_read_b128 v[202:205], v136 offset:37888
	ds_read_b128 v[236:239], v136 offset:38912
	ds_read_b128 v[240:243], v136 offset:39936
	s_waitcnt vmcnt(2)
	s_barrier
	s_waitcnt lgkmcnt(0)
	s_setprio 3
	s_waitcnt lgkmcnt(0)
	v_mfma_f32_16x16x32_bf16 v[30:33], v[66:69], v[182:185], v[30:33]
	v_mfma_f32_16x16x32_bf16 v[26:29], v[66:69], v[190:193], v[26:29]
	v_mfma_f32_16x16x32_bf16 v[22:25], v[82:85], v[182:185], v[22:25]
	v_mfma_f32_16x16x32_bf16 v[18:21], v[82:85], v[190:193], v[18:21]
	v_mfma_f32_16x16x32_bf16 v[14:17], v[198:201], v[182:185], v[14:17]
	v_mfma_f32_16x16x32_bf16 v[10:13], v[198:201], v[190:193], v[10:13]
	v_mfma_f32_16x16x32_bf16 v[6:9], v[236:239], v[182:185], v[6:9]
	v_mfma_f32_16x16x32_bf16 v[2:5], v[236:239], v[190:193], v[2:5]
	v_mfma_f32_16x16x32_bf16 v[122:125], v[70:73], v[186:189], v[30:33]
	v_mfma_f32_16x16x32_bf16 v[126:129], v[70:73], v[194:197], v[26:29]
	v_mfma_f32_16x16x32_bf16 v[106:109], v[86:89], v[186:189], v[22:25]
	v_mfma_f32_16x16x32_bf16 v[110:113], v[86:89], v[194:197], v[18:21]
	v_mfma_f32_16x16x32_bf16 v[90:93], v[202:205], v[186:189], v[14:17]
	v_mfma_f32_16x16x32_bf16 v[94:97], v[202:205], v[194:197], v[10:13]
	v_mfma_f32_16x16x32_bf16 v[74:77], v[240:243], v[186:189], v[6:9]
	v_mfma_f32_16x16x32_bf16 v[78:81], v[240:243], v[194:197], v[2:5]
	s_setprio 0
	s_barrier
	s_nop 0
	ds_read_b128 v[2:5], v137 offset:49152
	ds_read_b128 v[6:9], v137 offset:50176
	ds_read_b128 v[244:247], v137 offset:51200
	ds_read_b128 v[248:251], v137 offset:52224
	s_waitcnt vmcnt(0)
	s_barrier
	s_waitcnt lgkmcnt(0)
	s_setprio 3
	s_waitcnt lgkmcnt(0)
	v_mfma_f32_16x16x32_bf16 v[10:13], v[66:69], v[2:5], v[62:65]
	v_mfma_f32_16x16x32_bf16 v[114:117], v[70:73], v[6:9], v[10:13]
	v_mfma_f32_16x16x32_bf16 v[10:13], v[66:69], v[244:247], v[58:61]
	v_mfma_f32_16x16x32_bf16 v[118:121], v[70:73], v[248:251], v[10:13]
	v_mfma_f32_16x16x32_bf16 v[10:13], v[82:85], v[2:5], v[54:57]
	v_mfma_f32_16x16x32_bf16 v[98:101], v[86:89], v[6:9], v[10:13]
	v_mfma_f32_16x16x32_bf16 v[10:13], v[82:85], v[244:247], v[50:53]
	v_mfma_f32_16x16x32_bf16 v[102:105], v[86:89], v[248:251], v[10:13]
	v_mfma_f32_16x16x32_bf16 v[10:13], v[198:201], v[2:5], v[46:49]
	v_mfma_f32_16x16x32_bf16 v[82:85], v[202:205], v[6:9], v[10:13]
	v_mfma_f32_16x16x32_bf16 v[10:13], v[198:201], v[244:247], v[42:45]
	v_mfma_f32_16x16x32_bf16 v[86:89], v[202:205], v[248:251], v[10:13]
	v_mfma_f32_16x16x32_bf16 v[10:13], v[236:239], v[2:5], v[38:41]
	v_mfma_f32_16x16x32_bf16 v[66:69], v[240:243], v[6:9], v[10:13]
	v_mfma_f32_16x16x32_bf16 v[10:13], v[236:239], v[244:247], v[34:37]
	v_mfma_f32_16x16x32_bf16 v[70:73], v[240:243], v[248:251], v[10:13]
	s_setprio 0
	s_barrier
	ds_read_b128 v[18:21], v136 offset:49152
	ds_read_b128 v[22:25], v136 offset:50176
	ds_read_b128 v[38:41], v136 offset:51200
	ds_read_b128 v[198:201], v136 offset:52224
	ds_read_b128 v[202:205], v136 offset:53248
	ds_read_b128 v[236:239], v136 offset:54272
	ds_read_b128 v[240:243], v136 offset:55296
	ds_read_b128 v[138:141], v136 offset:56320
	s_barrier
	s_waitcnt lgkmcnt(0)
	s_setprio 3
	s_waitcnt lgkmcnt(0)
	v_mfma_f32_16x16x32_bf16 v[10:13], v[18:21], v[182:185], v[212:215]
	v_mfma_f32_16x16x32_bf16 v[58:61], v[22:25], v[186:189], v[10:13]
	v_mfma_f32_16x16x32_bf16 v[10:13], v[18:21], v[190:193], v[216:219]
	v_mfma_f32_16x16x32_bf16 v[62:65], v[22:25], v[194:197], v[10:13]
	v_mfma_f32_16x16x32_bf16 v[10:13], v[38:41], v[182:185], v[220:223]
	v_mfma_f32_16x16x32_bf16 v[42:45], v[198:201], v[186:189], v[10:13]
	v_mfma_f32_16x16x32_bf16 v[10:13], v[38:41], v[190:193], v[224:227]
	v_mfma_f32_16x16x32_bf16 v[46:49], v[198:201], v[194:197], v[10:13]
	v_mfma_f32_16x16x32_bf16 v[10:13], v[202:205], v[182:185], v[228:231]
	v_mfma_f32_16x16x32_bf16 v[26:29], v[236:239], v[186:189], v[10:13]
	v_mfma_f32_16x16x32_bf16 v[10:13], v[202:205], v[190:193], v[232:235]
	v_mfma_f32_16x16x32_bf16 v[30:33], v[236:239], v[194:197], v[10:13]
	v_mfma_f32_16x16x32_bf16 v[10:13], v[240:243], v[182:185], v[142:145]
	v_mfma_f32_16x16x32_bf16 v[14:17], v[240:243], v[190:193], v[146:149]
	v_mfma_f32_16x16x32_bf16 v[10:13], v[138:141], v[186:189], v[10:13]
	v_mfma_f32_16x16x32_bf16 v[14:17], v[138:141], v[194:197], v[14:17]
	s_setprio 0
	s_setprio 3
	v_mfma_f32_16x16x32_bf16 v[34:37], v[18:21], v[2:5], v[150:153]
	v_mfma_f32_16x16x32_bf16 v[18:21], v[18:21], v[244:247], v[154:157]
	v_mfma_f32_16x16x32_bf16 v[54:57], v[22:25], v[248:251], v[18:21]
	v_mfma_f32_16x16x32_bf16 v[18:21], v[38:41], v[2:5], v[158:161]
	v_mfma_f32_16x16x32_bf16 v[50:53], v[22:25], v[6:9], v[34:37]
	v_mfma_f32_16x16x32_bf16 v[34:37], v[198:201], v[6:9], v[18:21]
	v_mfma_f32_16x16x32_bf16 v[18:21], v[38:41], v[244:247], v[162:165]
	v_mfma_f32_16x16x32_bf16 v[38:41], v[198:201], v[248:251], v[18:21]
	v_mfma_f32_16x16x32_bf16 v[18:21], v[202:205], v[2:5], v[166:169]
	v_mfma_f32_16x16x32_bf16 v[2:5], v[240:243], v[2:5], v[174:177]
	v_mfma_f32_16x16x32_bf16 v[18:21], v[236:239], v[6:9], v[18:21]
	v_mfma_f32_16x16x32_bf16 v[22:25], v[202:205], v[244:247], v[170:173]
	v_mfma_f32_16x16x32_bf16 v[2:5], v[138:141], v[6:9], v[2:5]
	v_mfma_f32_16x16x32_bf16 v[6:9], v[240:243], v[244:247], v[178:181]
	v_mfma_f32_16x16x32_bf16 v[22:25], v[236:239], v[248:251], v[22:25]
	v_mfma_f32_16x16x32_bf16 v[6:9], v[138:141], v[248:251], v[6:9]
	s_setprio 0
	s_and_b64 vcc, exec, s[10:11]
	s_barrier
	s_cbranch_vccz .LBB0_367
	s_barrier

.LBB0_467:
	s_mul_hi_i32 s12, s49, 0x2e8ba2e9
	s_lshr_b32 s13, s12, 31
	s_ashr_i32 s12, s12, 5
	s_add_i32 s12, s12, s13
	s_mul_i32 s13, s12, 0xffffff50
	s_add_i32 s13, s13, s49
	s_ashr_i32 s50, s13, 3
	s_lshl_b32 s13, s49, 8
	s_lshl_b32 s12, s12, 11
	s_and_b32 s13, s13, 0x700
	s_or_b32 s12, s12, s13
	s_or_b32 s18, s12, 0x80
	s_ashr_i32 s19, s18, 31
	s_lshl_b32 s16, s50, 8
	s_lshl_b64 s[14:15], s[18:19], 10
	s_lshl_b64 s[18:19], s[18:19], 11
	s_add_u32 s18, s20, s18
	s_addc_u32 s19, s21, s19
	s_ashr_i32 s17, s16, 31
	s_lshl_b64 s[52:53], s[16:17], 11
	s_add_u32 s51, s22, s52
	s_addc_u32 s52, s23, s53
	s_ashr_i32 s13, s12, 31
	s_barrier
	s_barrier
	s_lshl_b64 s[54:55], s[12:13], 11
	ds_read_b128 v[2:5], v137
	ds_read_b128 v[6:9], v137 offset:1024
	ds_read_b128 v[10:13], v137 offset:2048
	ds_read_b128 v[14:17], v137 offset:3072
	s_add_u32 s13, s20, s54
	s_addc_u32 s53, s21, s55
	s_bitset1_b32 s16, 7
	s_ashr_i32 s17, s16, 31
	s_lshl_b64 s[16:17], s[16:17], 11
	s_add_u32 s54, s22, s16
	s_addc_u32 s55, s23, s17
	ds_read_b128 v[18:21], v136 offset:7168
	ds_read_b128 v[22:25], v136 offset:6144
	ds_read_b128 v[26:29], v136 offset:5120
	ds_read_b128 v[30:33], v136 offset:4096
	ds_read_b128 v[34:37], v136 offset:3072
	ds_read_b128 v[38:41], v136 offset:2048
	ds_read_b128 v[42:45], v136 offset:1024
	ds_read_b128 v[46:49], v136
	s_waitcnt lgkmcnt(8)
	s_barrier
	s_waitcnt lgkmcnt(0)
	s_setprio 3
	s_waitcnt lgkmcnt(0)
	v_mfma_f32_16x16x32_bf16 v[50:53], v[46:49], v[2:5], 0
	v_mfma_f32_16x16x32_bf16 v[54:57], v[46:49], v[10:13], 0
	v_mfma_f32_16x16x32_bf16 v[58:61], v[38:41], v[2:5], 0
	v_mfma_f32_16x16x32_bf16 v[62:65], v[38:41], v[10:13], 0
	v_mfma_f32_16x16x32_bf16 v[66:69], v[30:33], v[2:5], 0
	v_mfma_f32_16x16x32_bf16 v[70:73], v[30:33], v[10:13], 0
	v_mfma_f32_16x16x32_bf16 v[74:77], v[22:25], v[2:5], 0
	v_mfma_f32_16x16x32_bf16 v[78:81], v[22:25], v[10:13], 0
	v_mfma_f32_16x16x32_bf16 v[50:53], v[42:45], v[6:9], v[50:53]
	v_mfma_f32_16x16x32_bf16 v[54:57], v[42:45], v[14:17], v[54:57]
	v_mfma_f32_16x16x32_bf16 v[58:61], v[34:37], v[6:9], v[58:61]
	v_mfma_f32_16x16x32_bf16 v[62:65], v[34:37], v[14:17], v[62:65]
	v_mfma_f32_16x16x32_bf16 v[66:69], v[26:29], v[6:9], v[66:69]
	v_mfma_f32_16x16x32_bf16 v[70:73], v[26:29], v[14:17], v[70:73]
	v_mfma_f32_16x16x32_bf16 v[74:77], v[18:21], v[6:9], v[74:77]
	v_mfma_f32_16x16x32_bf16 v[78:81], v[18:21], v[14:17], v[78:81]
	s_setprio 0
	s_barrier
	s_add_u32 s16, s51, 0x100
	s_addc_u32 s17, s52, 0
	s_mov_b32 m0, s26
	ds_read_b128 v[82:85], v137 offset:16384
	ds_read_b128 v[86:89], v137 offset:17408
	ds_read_b128 v[90:93], v137 offset:18432
	ds_read_b128 v[94:97], v137 offset:19456
	s_nop 0
	global_load_lds_dwordx4 v130, s[16:17]
	s_mov_b32 m0, s27
	s_nop 0
	global_load_lds_dwordx4 v132, s[16:17]
	s_barrier
	s_waitcnt lgkmcnt(0)
	s_setprio 3
	s_waitcnt lgkmcnt(0)
	v_mfma_f32_16x16x32_bf16 v[98:101], v[46:49], v[82:85], 0
	v_mfma_f32_16x16x32_bf16 v[46:49], v[46:49], v[90:93], 0
	v_mfma_f32_16x16x32_bf16 v[98:101], v[42:45], v[86:89], v[98:101]
	v_mfma_f32_16x16x32_bf16 v[42:45], v[42:45], v[94:97], v[46:49]
	v_mfma_f32_16x16x32_bf16 v[46:49], v[38:41], v[82:85], 0
	v_mfma_f32_16x16x32_bf16 v[38:41], v[38:41], v[90:93], 0
	v_mfma_f32_16x16x32_bf16 v[46:49], v[34:37], v[86:89], v[46:49]
	v_mfma_f32_16x16x32_bf16 v[34:37], v[34:37], v[94:97], v[38:41]
	v_mfma_f32_16x16x32_bf16 v[38:41], v[30:33], v[82:85], 0
	v_mfma_f32_16x16x32_bf16 v[30:33], v[30:33], v[90:93], 0
	v_mfma_f32_16x16x32_bf16 v[38:41], v[26:29], v[86:89], v[38:41]
	v_mfma_f32_16x16x32_bf16 v[102:105], v[26:29], v[94:97], v[30:33]
	v_mfma_f32_16x16x32_bf16 v[26:29], v[22:25], v[82:85], 0
	v_mfma_f32_16x16x32_bf16 v[22:25], v[22:25], v[90:93], 0
	v_mfma_f32_16x16x32_bf16 v[106:109], v[18:21], v[86:89], v[26:29]
	v_mfma_f32_16x16x32_bf16 v[110:113], v[18:21], v[94:97], v[22:25]
	s_setprio 0
	s_add_u32 s16, s13, 0x100
	s_addc_u32 s17, s53, 0
	s_mov_b32 m0, s25
	s_barrier
	ds_read_b128 v[18:21], v136 offset:16384
	ds_read_b128 v[22:25], v136 offset:17408
	ds_read_b128 v[26:29], v136 offset:18432
	ds_read_b128 v[30:33], v136 offset:19456
	ds_read_b128 v[114:117], v136 offset:20480
	ds_read_b128 v[118:121], v136 offset:21504
	ds_read_b128 v[122:125], v136 offset:22528
	ds_read_b128 v[126:129], v136 offset:23552
	s_nop 0
	global_load_lds_dwordx4 v130, s[16:17]
	s_mov_b32 m0, s28
	s_nop 0
	global_load_lds_dwordx4 v132, s[16:17]
	s_barrier
	s_waitcnt lgkmcnt(0)
	s_setprio 3
	s_waitcnt lgkmcnt(0)
	v_mfma_f32_16x16x32_bf16 v[142:145], v[18:21], v[2:5], 0
	v_mfma_f32_16x16x32_bf16 v[150:153], v[26:29], v[2:5], 0
	v_mfma_f32_16x16x32_bf16 v[158:161], v[114:117], v[2:5], 0
	v_mfma_f32_16x16x32_bf16 v[2:5], v[122:125], v[2:5], 0
	v_mfma_f32_16x16x32_bf16 v[146:149], v[18:21], v[10:13], 0
	v_mfma_f32_16x16x32_bf16 v[154:157], v[26:29], v[10:13], 0
	v_mfma_f32_16x16x32_bf16 v[162:165], v[114:117], v[10:13], 0
	v_mfma_f32_16x16x32_bf16 v[166:169], v[126:129], v[6:9], v[2:5]
	v_mfma_f32_16x16x32_bf16 v[2:5], v[122:125], v[10:13], 0
	v_mfma_f32_16x16x32_bf16 v[142:145], v[22:25], v[6:9], v[142:145]
	v_mfma_f32_16x16x32_bf16 v[146:149], v[22:25], v[14:17], v[146:149]
	v_mfma_f32_16x16x32_bf16 v[150:153], v[30:33], v[6:9], v[150:153]
	v_mfma_f32_16x16x32_bf16 v[154:157], v[30:33], v[14:17], v[154:157]
	v_mfma_f32_16x16x32_bf16 v[158:161], v[118:121], v[6:9], v[158:161]
	v_mfma_f32_16x16x32_bf16 v[162:165], v[118:121], v[14:17], v[162:165]
	v_mfma_f32_16x16x32_bf16 v[170:173], v[126:129], v[14:17], v[2:5]
	s_setprio 0
	s_barrier
	s_add_u32 s16, s54, 0x100
	s_addc_u32 s17, s55, 0
	s_mov_b32 m0, s29
	s_nop 0
	global_load_lds_dwordx4 v130, s[16:17]
	s_mov_b32 m0, s30
	s_nop 0
	global_load_lds_dwordx4 v132, s[16:17]
	s_waitcnt vmcnt(14)
	s_barrier
	s_setprio 3
	v_mfma_f32_16x16x32_bf16 v[2:5], v[18:21], v[82:85], 0
	v_mfma_f32_16x16x32_bf16 v[174:177], v[22:25], v[86:89], v[2:5]
	v_mfma_f32_16x16x32_bf16 v[2:5], v[18:21], v[90:93], 0
	v_mfma_f32_16x16x32_bf16 v[178:181], v[22:25], v[94:97], v[2:5]
	v_mfma_f32_16x16x32_bf16 v[2:5], v[26:29], v[82:85], 0
	v_mfma_f32_16x16x32_bf16 v[182:185], v[30:33], v[86:89], v[2:5]
	v_mfma_f32_16x16x32_bf16 v[2:5], v[26:29], v[90:93], 0
	v_mfma_f32_16x16x32_bf16 v[186:189], v[30:33], v[94:97], v[2:5]
	v_mfma_f32_16x16x32_bf16 v[2:5], v[114:117], v[82:85], 0
	v_mfma_f32_16x16x32_bf16 v[190:193], v[118:121], v[86:89], v[2:5]
	v_mfma_f32_16x16x32_bf16 v[2:5], v[114:117], v[90:93], 0
	v_mfma_f32_16x16x32_bf16 v[194:197], v[118:121], v[94:97], v[2:5]
	v_mfma_f32_16x16x32_bf16 v[2:5], v[122:125], v[82:85], 0
	v_mfma_f32_16x16x32_bf16 v[198:201], v[126:129], v[86:89], v[2:5]
	v_mfma_f32_16x16x32_bf16 v[2:5], v[122:125], v[90:93], 0
	v_mfma_f32_16x16x32_bf16 v[202:205], v[126:129], v[94:97], v[2:5]
	s_setprio 0
	s_barrier
	ds_read_b128 v[114:117], v137 offset:32768
	ds_read_b128 v[118:121], v137 offset:33792
	ds_read_b128 v[122:125], v137 offset:34816
	ds_read_b128 v[126:129], v137 offset:35840
	s_add_u32 s16, s18, 0x100
	s_addc_u32 s17, s19, 0
	s_mov_b32 m0, s31
	ds_read_b128 v[82:85], v136 offset:32768
	ds_read_b128 v[86:89], v136 offset:33792
	ds_read_b128 v[90:93], v136 offset:34816
	ds_read_b128 v[94:97], v136 offset:35840
	ds_read_b128 v[216:219], v136 offset:36864
	ds_read_b128 v[220:223], v136 offset:37888
	ds_read_b128 v[224:227], v136 offset:38912
	ds_read_b128 v[228:231], v136 offset:39936
	s_nop 0
	global_load_lds_dwordx4 v130, s[16:17]
	s_mov_b32 m0, s33
	s_nop 0
	global_load_lds_dwordx4 v132, s[16:17]
	s_waitcnt lgkmcnt(8)
	s_barrier
	s_waitcnt lgkmcnt(0)
	s_setprio 3
	s_waitcnt lgkmcnt(0)
	v_mfma_f32_16x16x32_bf16 v[2:5], v[82:85], v[114:117], v[50:53]
	v_mfma_f32_16x16x32_bf16 v[30:33], v[86:89], v[118:121], v[2:5]
	v_mfma_f32_16x16x32_bf16 v[2:5], v[82:85], v[122:125], v[54:57]
	v_mfma_f32_16x16x32_bf16 v[26:29], v[86:89], v[126:129], v[2:5]
	v_mfma_f32_16x16x32_bf16 v[2:5], v[90:93], v[114:117], v[58:61]
	v_mfma_f32_16x16x32_bf16 v[22:25], v[94:97], v[118:121], v[2:5]
	v_mfma_f32_16x16x32_bf16 v[2:5], v[90:93], v[122:125], v[62:65]
	v_mfma_f32_16x16x32_bf16 v[18:21], v[94:97], v[126:129], v[2:5]
	v_mfma_f32_16x16x32_bf16 v[2:5], v[216:219], v[114:117], v[66:69]
	v_mfma_f32_16x16x32_bf16 v[14:17], v[220:223], v[118:121], v[2:5]
	v_mfma_f32_16x16x32_bf16 v[2:5], v[216:219], v[122:125], v[70:73]
	v_mfma_f32_16x16x32_bf16 v[10:13], v[220:223], v[126:129], v[2:5]
	v_mfma_f32_16x16x32_bf16 v[2:5], v[224:227], v[114:117], v[74:77]
	v_mfma_f32_16x16x32_bf16 v[6:9], v[228:231], v[118:121], v[2:5]
	v_mfma_f32_16x16x32_bf16 v[2:5], v[224:227], v[122:125], v[78:81]
	v_mfma_f32_16x16x32_bf16 v[2:5], v[228:231], v[126:129], v[2:5]
	s_setprio 0
	s_barrier
	s_add_u32 s16, s51, 0x180
	s_addc_u32 s17, s52, 0
	s_mov_b32 m0, s34
	ds_read_b128 v[232:235], v137 offset:49152
	ds_read_b128 v[236:239], v137 offset:50176
	ds_read_b128 v[240:243], v137 offset:51200
	ds_read_b128 v[244:247], v137 offset:52224
	s_nop 0
	global_load_lds_dwordx4 v130, s[16:17]
	s_mov_b32 m0, s35
	s_nop 0
	global_load_lds_dwordx4 v132, s[16:17]
	s_barrier
	s_waitcnt lgkmcnt(0)
	s_setprio 3
	s_waitcnt lgkmcnt(0)
	v_mfma_f32_16x16x32_bf16 v[50:53], v[82:85], v[232:235], v[98:101]
	v_mfma_f32_16x16x32_bf16 v[34:37], v[90:93], v[240:243], v[34:37]
	v_mfma_f32_16x16x32_bf16 v[62:65], v[86:89], v[236:239], v[50:53]
	v_mfma_f32_16x16x32_bf16 v[42:45], v[82:85], v[240:243], v[42:45]
	v_mfma_f32_16x16x32_bf16 v[50:53], v[94:97], v[244:247], v[34:37]
	v_mfma_f32_16x16x32_bf16 v[34:37], v[216:219], v[232:235], v[38:41]
	v_mfma_f32_16x16x32_bf16 v[58:61], v[86:89], v[244:247], v[42:45]
	v_mfma_f32_16x16x32_bf16 v[42:45], v[90:93], v[232:235], v[46:49]
	v_mfma_f32_16x16x32_bf16 v[46:49], v[220:223], v[236:239], v[34:37]
	v_mfma_f32_16x16x32_bf16 v[34:37], v[216:219], v[240:243], v[102:105]
	v_mfma_f32_16x16x32_bf16 v[54:57], v[94:97], v[236:239], v[42:45]
	v_mfma_f32_16x16x32_bf16 v[42:45], v[220:223], v[244:247], v[34:37]
	v_mfma_f32_16x16x32_bf16 v[34:37], v[224:227], v[232:235], v[106:109]
	v_mfma_f32_16x16x32_bf16 v[38:41], v[228:231], v[236:239], v[34:37]
	v_mfma_f32_16x16x32_bf16 v[34:37], v[224:227], v[240:243], v[110:113]
	v_mfma_f32_16x16x32_bf16 v[34:37], v[228:231], v[244:247], v[34:37]
	s_setprio 0
	s_add_u32 s16, s13, 0x180
	s_addc_u32 s17, s53, 0
	s_mov_b32 m0, s36
	s_barrier
	ds_read_b128 v[98:101], v136 offset:49152
	ds_read_b128 v[102:105], v136 offset:50176
	ds_read_b128 v[106:109], v136 offset:51200
	ds_read_b128 v[110:113], v136 offset:52224
	ds_read_b128 v[216:219], v136 offset:53248
	ds_read_b128 v[220:223], v136 offset:54272
	ds_read_b128 v[224:227], v136 offset:55296
	ds_read_b128 v[228:231], v136 offset:56320
	s_nop 0
	global_load_lds_dwordx4 v130, s[16:17]
	s_mov_b32 m0, s37
	s_nop 0
	global_load_lds_dwordx4 v132, s[16:17]
	s_waitcnt vmcnt(10)
	s_barrier
	s_waitcnt lgkmcnt(0)
	s_setprio 3
	s_waitcnt lgkmcnt(0)
	v_mfma_f32_16x16x32_bf16 v[66:69], v[98:101], v[114:117], v[142:145]
	v_mfma_f32_16x16x32_bf16 v[94:97], v[102:105], v[118:121], v[66:69]
	v_mfma_f32_16x16x32_bf16 v[66:69], v[98:101], v[122:125], v[146:149]
	v_mfma_f32_16x16x32_bf16 v[90:93], v[102:105], v[126:129], v[66:69]
	v_mfma_f32_16x16x32_bf16 v[66:69], v[106:109], v[114:117], v[150:153]
	v_mfma_f32_16x16x32_bf16 v[86:89], v[110:113], v[118:121], v[66:69]
	v_mfma_f32_16x16x32_bf16 v[66:69], v[106:109], v[122:125], v[154:157]
	v_mfma_f32_16x16x32_bf16 v[82:85], v[110:113], v[126:129], v[66:69]
	v_mfma_f32_16x16x32_bf16 v[66:69], v[216:219], v[114:117], v[158:161]
	v_mfma_f32_16x16x32_bf16 v[78:81], v[220:223], v[118:121], v[66:69]
	v_mfma_f32_16x16x32_bf16 v[66:69], v[216:219], v[122:125], v[162:165]
	v_mfma_f32_16x16x32_bf16 v[74:77], v[220:223], v[126:129], v[66:69]
	v_mfma_f32_16x16x32_bf16 v[66:69], v[224:227], v[114:117], v[166:169]
	v_mfma_f32_16x16x32_bf16 v[70:73], v[228:231], v[118:121], v[66:69]
	v_mfma_f32_16x16x32_bf16 v[66:69], v[224:227], v[122:125], v[170:173]
	v_mfma_f32_16x16x32_bf16 v[66:69], v[228:231], v[126:129], v[66:69]
	s_setprio 0
	s_barrier
	s_add_u32 s16, s54, 0x180
	s_addc_u32 s17, s55, 0
	s_mov_b32 m0, s38
	s_nop 0
	global_load_lds_dwordx4 v130, s[16:17]
	s_mov_b32 m0, s39
	s_nop 0
	global_load_lds_dwordx4 v132, s[16:17]
	ds_read_b128 v[138:141], v137
	ds_read_b128 v[142:145], v137 offset:1024
	ds_read_b128 v[146:149], v137 offset:2048
	ds_read_b128 v[150:153], v137 offset:3072
	s_waitcnt vmcnt(6)
	s_barrier
	s_setprio 3
	v_mfma_f32_16x16x32_bf16 v[114:117], v[98:101], v[232:235], v[174:177]
	v_mfma_f32_16x16x32_bf16 v[98:101], v[98:101], v[240:243], v[178:181]
	v_mfma_f32_16x16x32_bf16 v[122:125], v[102:105], v[244:247], v[98:101]
	v_mfma_f32_16x16x32_bf16 v[98:101], v[106:109], v[232:235], v[182:185]
	v_mfma_f32_16x16x32_bf16 v[118:121], v[110:113], v[236:239], v[98:101]
	v_mfma_f32_16x16x32_bf16 v[98:101], v[106:109], v[240:243], v[186:189]
	v_mfma_f32_16x16x32_bf16 v[126:129], v[102:105], v[236:239], v[114:117]
	v_mfma_f32_16x16x32_bf16 v[114:117], v[110:113], v[244:247], v[98:101]
	v_mfma_f32_16x16x32_bf16 v[98:101], v[216:219], v[232:235], v[190:193]
	v_mfma_f32_16x16x32_bf16 v[110:113], v[220:223], v[236:239], v[98:101]
	v_mfma_f32_16x16x32_bf16 v[98:101], v[216:219], v[240:243], v[194:197]
	v_mfma_f32_16x16x32_bf16 v[106:109], v[220:223], v[244:247], v[98:101]
	v_mfma_f32_16x16x32_bf16 v[98:101], v[224:227], v[232:235], v[198:201]
	v_mfma_f32_16x16x32_bf16 v[102:105], v[228:231], v[236:239], v[98:101]
	v_mfma_f32_16x16x32_bf16 v[98:101], v[224:227], v[240:243], v[202:205]
	v_mfma_f32_16x16x32_bf16 v[98:101], v[228:231], v[244:247], v[98:101]
	s_setprio 0
	s_mov_b32 s56, 0
	s_mov_b64 s[16:17], 0
	s_barrier
.LBB0_468:
	s_add_u32 s57, s18, s16
	s_addc_u32 s60, s19, s17
	s_add_u32 s58, s57, 0x180
	s_addc_u32 s59, s60, 0
	s_mov_b32 m0, s40
	ds_read_b128 v[154:157], v136
	ds_read_b128 v[158:161], v136 offset:1024
	ds_read_b128 v[162:165], v136 offset:2048
	ds_read_b128 v[166:169], v136 offset:3072
	ds_read_b128 v[170:173], v136 offset:4096
	ds_read_b128 v[174:177], v136 offset:5120
	ds_read_b128 v[178:181], v136 offset:6144
	ds_read_b128 v[182:185], v136 offset:7168
	s_nop 0
	global_load_lds_dwordx4 v130, s[58:59]
	s_mov_b32 m0, s41
	s_nop 0
	global_load_lds_dwordx4 v132, s[58:59]
	s_waitcnt lgkmcnt(8)
	s_barrier
	s_waitcnt lgkmcnt(0)
	s_setprio 3
	s_waitcnt lgkmcnt(0)
	v_mfma_f32_16x16x32_bf16 v[30:33], v[154:157], v[138:141], v[30:33]
	v_mfma_f32_16x16x32_bf16 v[26:29], v[154:157], v[146:149], v[26:29]
	v_mfma_f32_16x16x32_bf16 v[22:25], v[162:165], v[138:141], v[22:25]
	v_mfma_f32_16x16x32_bf16 v[18:21], v[162:165], v[146:149], v[18:21]
	v_mfma_f32_16x16x32_bf16 v[14:17], v[170:173], v[138:141], v[14:17]
	v_mfma_f32_16x16x32_bf16 v[10:13], v[170:173], v[146:149], v[10:13]
	v_mfma_f32_16x16x32_bf16 v[6:9], v[178:181], v[138:141], v[6:9]
	v_mfma_f32_16x16x32_bf16 v[2:5], v[178:181], v[146:149], v[2:5]
	v_mfma_f32_16x16x32_bf16 v[30:33], v[158:161], v[142:145], v[30:33]
	v_mfma_f32_16x16x32_bf16 v[26:29], v[158:161], v[150:153], v[26:29]
	v_mfma_f32_16x16x32_bf16 v[22:25], v[166:169], v[142:145], v[22:25]
	v_mfma_f32_16x16x32_bf16 v[18:21], v[166:169], v[150:153], v[18:21]
	v_mfma_f32_16x16x32_bf16 v[14:17], v[174:177], v[142:145], v[14:17]
	v_mfma_f32_16x16x32_bf16 v[10:13], v[174:177], v[150:153], v[10:13]
	v_mfma_f32_16x16x32_bf16 v[6:9], v[182:185], v[142:145], v[6:9]
	v_mfma_f32_16x16x32_bf16 v[2:5], v[182:185], v[150:153], v[2:5]
	s_setprio 0
	s_barrier
	s_add_u32 s61, s51, s16
	s_addc_u32 s62, s52, s17
	s_add_u32 s58, s61, 0x200
	s_addc_u32 s59, s62, 0
	s_mov_b32 m0, s26
	ds_read_b128 v[186:189], v137 offset:16384
	ds_read_b128 v[190:193], v137 offset:17408
	ds_read_b128 v[194:197], v137 offset:18432
	ds_read_b128 v[198:201], v137 offset:19456
	s_nop 0
	global_load_lds_dwordx4 v130, s[58:59]
	s_mov_b32 m0, s27
	s_nop 0
	global_load_lds_dwordx4 v132, s[58:59]
	s_barrier
	s_waitcnt lgkmcnt(0)
	s_setprio 3
	s_waitcnt lgkmcnt(0)
	v_mfma_f32_16x16x32_bf16 v[62:65], v[154:157], v[186:189], v[62:65]
	v_mfma_f32_16x16x32_bf16 v[58:61], v[154:157], v[194:197], v[58:61]
	v_mfma_f32_16x16x32_bf16 v[54:57], v[162:165], v[186:189], v[54:57]
	v_mfma_f32_16x16x32_bf16 v[50:53], v[162:165], v[194:197], v[50:53]
	v_mfma_f32_16x16x32_bf16 v[46:49], v[170:173], v[186:189], v[46:49]
	v_mfma_f32_16x16x32_bf16 v[42:45], v[170:173], v[194:197], v[42:45]
	v_mfma_f32_16x16x32_bf16 v[38:41], v[178:181], v[186:189], v[38:41]
	v_mfma_f32_16x16x32_bf16 v[34:37], v[178:181], v[194:197], v[34:37]
	v_mfma_f32_16x16x32_bf16 v[62:65], v[158:161], v[190:193], v[62:65]
	v_mfma_f32_16x16x32_bf16 v[58:61], v[158:161], v[198:201], v[58:61]
	v_mfma_f32_16x16x32_bf16 v[54:57], v[166:169], v[190:193], v[54:57]
	v_mfma_f32_16x16x32_bf16 v[50:53], v[166:169], v[198:201], v[50:53]
	v_mfma_f32_16x16x32_bf16 v[46:49], v[174:177], v[190:193], v[46:49]
	v_mfma_f32_16x16x32_bf16 v[42:45], v[174:177], v[198:201], v[42:45]
	v_mfma_f32_16x16x32_bf16 v[38:41], v[182:185], v[190:193], v[38:41]
	v_mfma_f32_16x16x32_bf16 v[34:37], v[182:185], v[198:201], v[34:37]
	s_setprio 0
	s_add_u32 s63, s13, s16
	s_addc_u32 s64, s53, s17
	s_add_u32 s58, s63, 0x200
	s_addc_u32 s59, s64, 0
	s_mov_b32 m0, s25
	s_barrier
	ds_read_b128 v[154:157], v136 offset:16384
	ds_read_b128 v[158:161], v136 offset:17408
	ds_read_b128 v[162:165], v136 offset:18432
	ds_read_b128 v[166:169], v136 offset:19456
	ds_read_b128 v[170:173], v136 offset:20480
	ds_read_b128 v[174:177], v136 offset:21504
	ds_read_b128 v[178:181], v136 offset:22528
	ds_read_b128 v[182:185], v136 offset:23552
	s_nop 0
	global_load_lds_dwordx4 v130, s[58:59]
	s_mov_b32 m0, s28
	s_nop 0
	global_load_lds_dwordx4 v132, s[58:59]
	s_waitcnt vmcnt(10)
	s_barrier
	s_waitcnt lgkmcnt(0)
	s_setprio 3
	s_waitcnt lgkmcnt(0)
	v_mfma_f32_16x16x32_bf16 v[94:97], v[154:157], v[138:141], v[94:97]
	v_mfma_f32_16x16x32_bf16 v[90:93], v[154:157], v[146:149], v[90:93]
	v_mfma_f32_16x16x32_bf16 v[86:89], v[162:165], v[138:141], v[86:89]
	v_mfma_f32_16x16x32_bf16 v[82:85], v[162:165], v[146:149], v[82:85]
	v_mfma_f32_16x16x32_bf16 v[78:81], v[170:173], v[138:141], v[78:81]
	v_mfma_f32_16x16x32_bf16 v[74:77], v[170:173], v[146:149], v[74:77]
	v_mfma_f32_16x16x32_bf16 v[70:73], v[178:181], v[138:141], v[70:73]
	v_mfma_f32_16x16x32_bf16 v[66:69], v[178:181], v[146:149], v[66:69]
	v_mfma_f32_16x16x32_bf16 v[94:97], v[158:161], v[142:145], v[94:97]
	v_mfma_f32_16x16x32_bf16 v[90:93], v[158:161], v[150:153], v[90:93]
	v_mfma_f32_16x16x32_bf16 v[86:89], v[166:169], v[142:145], v[86:89]
	v_mfma_f32_16x16x32_bf16 v[82:85], v[166:169], v[150:153], v[82:85]
	v_mfma_f32_16x16x32_bf16 v[78:81], v[174:177], v[142:145], v[78:81]
	v_mfma_f32_16x16x32_bf16 v[74:77], v[174:177], v[150:153], v[74:77]
	v_mfma_f32_16x16x32_bf16 v[70:73], v[182:185], v[142:145], v[70:73]
	v_mfma_f32_16x16x32_bf16 v[66:69], v[182:185], v[150:153], v[66:69]
	s_setprio 0
	s_barrier
	s_add_u32 s65, s54, s16
	s_addc_u32 s66, s55, s17
	s_add_u32 s58, s65, 0x200
	s_addc_u32 s59, s66, 0
	s_mov_b32 m0, s29
	s_nop 0
	global_load_lds_dwordx4 v130, s[58:59]
	s_mov_b32 m0, s30
	s_nop 0
	global_load_lds_dwordx4 v132, s[58:59]
	ds_read_b128 v[138:141], v137 offset:32768
	ds_read_b128 v[142:145], v137 offset:33792
	ds_read_b128 v[146:149], v137 offset:34816
	ds_read_b128 v[150:153], v137 offset:35840
	s_waitcnt vmcnt(6)
	s_barrier
	s_setprio 3
	v_mfma_f32_16x16x32_bf16 v[126:129], v[154:157], v[186:189], v[126:129]
	v_mfma_f32_16x16x32_bf16 v[122:125], v[154:157], v[194:197], v[122:125]
	v_mfma_f32_16x16x32_bf16 v[118:121], v[162:165], v[186:189], v[118:121]
	v_mfma_f32_16x16x32_bf16 v[114:117], v[162:165], v[194:197], v[114:117]
	v_mfma_f32_16x16x32_bf16 v[110:113], v[170:173], v[186:189], v[110:113]
	v_mfma_f32_16x16x32_bf16 v[106:109], v[170:173], v[194:197], v[106:109]
	v_mfma_f32_16x16x32_bf16 v[102:105], v[178:181], v[186:189], v[102:105]
	v_mfma_f32_16x16x32_bf16 v[98:101], v[178:181], v[194:197], v[98:101]
	v_mfma_f32_16x16x32_bf16 v[126:129], v[158:161], v[190:193], v[126:129]
	v_mfma_f32_16x16x32_bf16 v[122:125], v[158:161], v[198:201], v[122:125]
	v_mfma_f32_16x16x32_bf16 v[118:121], v[166:169], v[190:193], v[118:121]
	v_mfma_f32_16x16x32_bf16 v[114:117], v[166:169], v[198:201], v[114:117]
	v_mfma_f32_16x16x32_bf16 v[110:113], v[174:177], v[190:193], v[110:113]
	v_mfma_f32_16x16x32_bf16 v[106:109], v[174:177], v[198:201], v[106:109]
	v_mfma_f32_16x16x32_bf16 v[102:105], v[182:185], v[190:193], v[102:105]
	v_mfma_f32_16x16x32_bf16 v[98:101], v[182:185], v[198:201], v[98:101]
	s_setprio 0
	s_barrier
	s_add_u32 s58, s57, 0x200
	s_addc_u32 s59, s60, 0
	s_mov_b32 m0, s31
	ds_read_b128 v[154:157], v136 offset:32768
	ds_read_b128 v[158:161], v136 offset:33792
	ds_read_b128 v[162:165], v136 offset:34816
	ds_read_b128 v[166:169], v136 offset:35840
	ds_read_b128 v[170:173], v136 offset:36864
	ds_read_b128 v[174:177], v136 offset:37888
	ds_read_b128 v[178:181], v136 offset:38912
	ds_read_b128 v[182:185], v136 offset:39936
	s_nop 0
	global_load_lds_dwordx4 v130, s[58:59]
	s_mov_b32 m0, s33
	s_nop 0
	global_load_lds_dwordx4 v132, s[58:59]
	s_waitcnt lgkmcnt(8)
	s_barrier
	s_waitcnt lgkmcnt(0)
	s_setprio 3
	s_waitcnt lgkmcnt(0)
	v_mfma_f32_16x16x32_bf16 v[30:33], v[154:157], v[138:141], v[30:33]
	v_mfma_f32_16x16x32_bf16 v[26:29], v[154:157], v[146:149], v[26:29]
	v_mfma_f32_16x16x32_bf16 v[22:25], v[162:165], v[138:141], v[22:25]
	v_mfma_f32_16x16x32_bf16 v[18:21], v[162:165], v[146:149], v[18:21]
	v_mfma_f32_16x16x32_bf16 v[14:17], v[170:173], v[138:141], v[14:17]
	v_mfma_f32_16x16x32_bf16 v[10:13], v[170:173], v[146:149], v[10:13]
	v_mfma_f32_16x16x32_bf16 v[6:9], v[178:181], v[138:141], v[6:9]
	v_mfma_f32_16x16x32_bf16 v[2:5], v[178:181], v[146:149], v[2:5]
	v_mfma_f32_16x16x32_bf16 v[30:33], v[158:161], v[142:145], v[30:33]
	v_mfma_f32_16x16x32_bf16 v[26:29], v[158:161], v[150:153], v[26:29]
	v_mfma_f32_16x16x32_bf16 v[22:25], v[166:169], v[142:145], v[22:25]
	v_mfma_f32_16x16x32_bf16 v[18:21], v[166:169], v[150:153], v[18:21]
	v_mfma_f32_16x16x32_bf16 v[14:17], v[174:177], v[142:145], v[14:17]
	v_mfma_f32_16x16x32_bf16 v[10:13], v[174:177], v[150:153], v[10:13]
	v_mfma_f32_16x16x32_bf16 v[6:9], v[182:185], v[142:145], v[6:9]
	v_mfma_f32_16x16x32_bf16 v[2:5], v[182:185], v[150:153], v[2:5]
	s_setprio 0
	s_barrier
	s_add_u32 s58, s61, 0x280
	s_addc_u32 s59, s62, 0
	s_mov_b32 m0, s34
	ds_read_b128 v[186:189], v137 offset:49152
	ds_read_b128 v[190:193], v137 offset:50176
	ds_read_b128 v[194:197], v137 offset:51200
	ds_read_b128 v[198:201], v137 offset:52224
	s_nop 0
	global_load_lds_dwordx4 v130, s[58:59]
	s_mov_b32 m0, s35
	s_nop 0
	global_load_lds_dwordx4 v132, s[58:59]
	s_barrier
	s_waitcnt lgkmcnt(0)
	s_setprio 3
	s_waitcnt lgkmcnt(0)
	v_mfma_f32_16x16x32_bf16 v[62:65], v[154:157], v[186:189], v[62:65]
	v_mfma_f32_16x16x32_bf16 v[58:61], v[154:157], v[194:197], v[58:61]
	v_mfma_f32_16x16x32_bf16 v[54:57], v[162:165], v[186:189], v[54:57]
	v_mfma_f32_16x16x32_bf16 v[50:53], v[162:165], v[194:197], v[50:53]
	v_mfma_f32_16x16x32_bf16 v[46:49], v[170:173], v[186:189], v[46:49]
	v_mfma_f32_16x16x32_bf16 v[42:45], v[170:173], v[194:197], v[42:45]
	v_mfma_f32_16x16x32_bf16 v[38:41], v[178:181], v[186:189], v[38:41]
	v_mfma_f32_16x16x32_bf16 v[34:37], v[178:181], v[194:197], v[34:37]
	v_mfma_f32_16x16x32_bf16 v[62:65], v[158:161], v[190:193], v[62:65]
	v_mfma_f32_16x16x32_bf16 v[58:61], v[158:161], v[198:201], v[58:61]
	v_mfma_f32_16x16x32_bf16 v[54:57], v[166:169], v[190:193], v[54:57]
	v_mfma_f32_16x16x32_bf16 v[50:53], v[166:169], v[198:201], v[50:53]
	v_mfma_f32_16x16x32_bf16 v[46:49], v[174:177], v[190:193], v[46:49]
	v_mfma_f32_16x16x32_bf16 v[42:45], v[174:177], v[198:201], v[42:45]
	v_mfma_f32_16x16x32_bf16 v[38:41], v[182:185], v[190:193], v[38:41]
	v_mfma_f32_16x16x32_bf16 v[34:37], v[182:185], v[198:201], v[34:37]
	s_setprio 0
	s_add_u32 s58, s63, 0x280
	s_addc_u32 s59, s64, 0
	s_mov_b32 m0, s36
	s_barrier
	ds_read_b128 v[154:157], v136 offset:49152
	ds_read_b128 v[158:161], v136 offset:50176
	ds_read_b128 v[162:165], v136 offset:51200
	ds_read_b128 v[166:169], v136 offset:52224
	ds_read_b128 v[170:173], v136 offset:53248
	ds_read_b128 v[174:177], v136 offset:54272
	ds_read_b128 v[178:181], v136 offset:55296
	ds_read_b128 v[182:185], v136 offset:56320
	s_nop 0
	global_load_lds_dwordx4 v130, s[58:59]
	s_mov_b32 m0, s37
	s_nop 0
	global_load_lds_dwordx4 v132, s[58:59]
	s_waitcnt vmcnt(10)
	s_barrier
	s_waitcnt lgkmcnt(0)
	s_setprio 3
	s_waitcnt lgkmcnt(0)
	v_mfma_f32_16x16x32_bf16 v[94:97], v[154:157], v[138:141], v[94:97]
	v_mfma_f32_16x16x32_bf16 v[90:93], v[154:157], v[146:149], v[90:93]
	v_mfma_f32_16x16x32_bf16 v[86:89], v[162:165], v[138:141], v[86:89]
	v_mfma_f32_16x16x32_bf16 v[82:85], v[162:165], v[146:149], v[82:85]
	v_mfma_f32_16x16x32_bf16 v[78:81], v[170:173], v[138:141], v[78:81]
	v_mfma_f32_16x16x32_bf16 v[74:77], v[170:173], v[146:149], v[74:77]
	v_mfma_f32_16x16x32_bf16 v[70:73], v[178:181], v[138:141], v[70:73]
	v_mfma_f32_16x16x32_bf16 v[66:69], v[178:181], v[146:149], v[66:69]
	v_mfma_f32_16x16x32_bf16 v[94:97], v[158:161], v[142:145], v[94:97]
	v_mfma_f32_16x16x32_bf16 v[90:93], v[158:161], v[150:153], v[90:93]
	v_mfma_f32_16x16x32_bf16 v[86:89], v[166:169], v[142:145], v[86:89]
	v_mfma_f32_16x16x32_bf16 v[82:85], v[166:169], v[150:153], v[82:85]
	v_mfma_f32_16x16x32_bf16 v[78:81], v[174:177], v[142:145], v[78:81]
	v_mfma_f32_16x16x32_bf16 v[74:77], v[174:177], v[150:153], v[74:77]
	v_mfma_f32_16x16x32_bf16 v[70:73], v[182:185], v[142:145], v[70:73]
	v_mfma_f32_16x16x32_bf16 v[66:69], v[182:185], v[150:153], v[66:69]
	s_setprio 0
	s_barrier
	s_add_u32 s58, s65, 0x280
	s_addc_u32 s59, s66, 0
	s_mov_b32 m0, s38
	s_nop 0
	global_load_lds_dwordx4 v130, s[58:59]
	s_mov_b32 m0, s39
	s_nop 0
	global_load_lds_dwordx4 v132, s[58:59]
	ds_read_b128 v[138:141], v137
	ds_read_b128 v[142:145], v137 offset:1024
	ds_read_b128 v[146:149], v137 offset:2048
	ds_read_b128 v[150:153], v137 offset:3072
	s_waitcnt vmcnt(6)
	s_barrier
	s_setprio 3
	v_mfma_f32_16x16x32_bf16 v[126:129], v[154:157], v[186:189], v[126:129]
	v_mfma_f32_16x16x32_bf16 v[122:125], v[154:157], v[194:197], v[122:125]
	v_mfma_f32_16x16x32_bf16 v[118:121], v[162:165], v[186:189], v[118:121]
	v_mfma_f32_16x16x32_bf16 v[114:117], v[162:165], v[194:197], v[114:117]
	v_mfma_f32_16x16x32_bf16 v[110:113], v[170:173], v[186:189], v[110:113]
	v_mfma_f32_16x16x32_bf16 v[106:109], v[170:173], v[194:197], v[106:109]
	v_mfma_f32_16x16x32_bf16 v[102:105], v[178:181], v[186:189], v[102:105]
	v_mfma_f32_16x16x32_bf16 v[98:101], v[178:181], v[194:197], v[98:101]
	v_mfma_f32_16x16x32_bf16 v[126:129], v[158:161], v[190:193], v[126:129]
	v_mfma_f32_16x16x32_bf16 v[122:125], v[158:161], v[198:201], v[122:125]
	v_mfma_f32_16x16x32_bf16 v[118:121], v[166:169], v[190:193], v[118:121]
	v_mfma_f32_16x16x32_bf16 v[114:117], v[166:169], v[198:201], v[114:117]
	v_mfma_f32_16x16x32_bf16 v[110:113], v[174:177], v[190:193], v[110:113]
	v_mfma_f32_16x16x32_bf16 v[106:109], v[174:177], v[198:201], v[106:109]
	v_mfma_f32_16x16x32_bf16 v[102:105], v[182:185], v[190:193], v[102:105]
	v_mfma_f32_16x16x32_bf16 v[98:101], v[182:185], v[198:201], v[98:101]
	s_setprio 0
	s_add_i32 s56, s56, 2
	s_add_u32 s16, s16, 0x100
	s_addc_u32 s17, s17, 0
	s_cmp_gt_u32 s56, 11
	s_barrier
	s_cbranch_scc0 .LBB0_468
	s_lshl_b64 s[14:15], s[14:15], 1
	s_add_u32 s14, s42, s14
	s_addc_u32 s15, s43, s15
	s_mov_b32 m0, s40
	ds_read_b128 v[142:145], v137
	ds_read_b128 v[146:149], v137 offset:1024
	ds_read_b128 v[150:153], v137 offset:2048
	ds_read_b128 v[154:157], v137 offset:3072
	ds_read_b128 v[158:161], v136
	ds_read_b128 v[162:165], v136 offset:1024
	ds_read_b128 v[166:169], v136 offset:2048
	ds_read_b128 v[170:173], v136 offset:3072
	ds_read_b128 v[174:177], v136 offset:4096
	ds_read_b128 v[178:181], v136 offset:5120
	ds_read_b128 v[182:185], v136 offset:6144
	ds_read_b128 v[186:189], v136 offset:7168
	s_nop 0
	global_load_lds_dwordx4 v130, s[14:15]
	s_mov_b32 m0, s41
	s_nop 0
	global_load_lds_dwordx4 v132, s[14:15]
	s_barrier
	s_waitcnt lgkmcnt(0)
	s_setprio 3
	s_waitcnt lgkmcnt(0)
	v_mfma_f32_16x16x32_bf16 v[30:33], v[158:161], v[142:145], v[30:33]
	v_mfma_f32_16x16x32_bf16 v[26:29], v[158:161], v[150:153], v[26:29]
	v_mfma_f32_16x16x32_bf16 v[22:25], v[166:169], v[142:145], v[22:25]
	v_mfma_f32_16x16x32_bf16 v[18:21], v[166:169], v[150:153], v[18:21]
	v_mfma_f32_16x16x32_bf16 v[14:17], v[174:177], v[142:145], v[14:17]
	v_mfma_f32_16x16x32_bf16 v[10:13], v[174:177], v[150:153], v[10:13]
	v_mfma_f32_16x16x32_bf16 v[6:9], v[182:185], v[142:145], v[6:9]
	v_mfma_f32_16x16x32_bf16 v[2:5], v[182:185], v[150:153], v[2:5]
	v_mfma_f32_16x16x32_bf16 v[30:33], v[162:165], v[146:149], v[30:33]
	v_mfma_f32_16x16x32_bf16 v[26:29], v[162:165], v[154:157], v[26:29]
	v_mfma_f32_16x16x32_bf16 v[22:25], v[170:173], v[146:149], v[22:25]
	v_mfma_f32_16x16x32_bf16 v[18:21], v[170:173], v[154:157], v[18:21]
	v_mfma_f32_16x16x32_bf16 v[14:17], v[178:181], v[146:149], v[14:17]
	v_mfma_f32_16x16x32_bf16 v[10:13], v[178:181], v[154:157], v[10:13]
	v_mfma_f32_16x16x32_bf16 v[6:9], v[186:189], v[146:149], v[6:9]
	v_mfma_f32_16x16x32_bf16 v[2:5], v[186:189], v[154:157], v[2:5]
	s_setprio 0
	s_barrier
	ds_read_b128 v[190:193], v137 offset:16384
	ds_read_b128 v[194:197], v137 offset:17408
	ds_read_b128 v[198:201], v137 offset:18432
	ds_read_b128 v[202:205], v137 offset:19456
	s_barrier
	s_waitcnt lgkmcnt(0)
	s_setprio 3
	s_waitcnt lgkmcnt(0)
	v_mfma_f32_16x16x32_bf16 v[62:65], v[158:161], v[190:193], v[62:65]
	v_mfma_f32_16x16x32_bf16 v[58:61], v[158:161], v[198:201], v[58:61]
	v_mfma_f32_16x16x32_bf16 v[54:57], v[166:169], v[190:193], v[54:57]
	v_mfma_f32_16x16x32_bf16 v[50:53], v[166:169], v[198:201], v[50:53]
	v_mfma_f32_16x16x32_bf16 v[46:49], v[174:177], v[190:193], v[46:49]
	v_mfma_f32_16x16x32_bf16 v[42:45], v[174:177], v[198:201], v[42:45]
	v_mfma_f32_16x16x32_bf16 v[38:41], v[182:185], v[190:193], v[38:41]
	v_mfma_f32_16x16x32_bf16 v[34:37], v[182:185], v[198:201], v[34:37]
	v_mfma_f32_16x16x32_bf16 v[62:65], v[162:165], v[194:197], v[62:65]
	v_mfma_f32_16x16x32_bf16 v[58:61], v[162:165], v[202:205], v[58:61]
	v_mfma_f32_16x16x32_bf16 v[54:57], v[170:173], v[194:197], v[54:57]
	v_mfma_f32_16x16x32_bf16 v[50:53], v[170:173], v[202:205], v[50:53]
	v_mfma_f32_16x16x32_bf16 v[46:49], v[178:181], v[194:197], v[46:49]
	v_mfma_f32_16x16x32_bf16 v[42:45], v[178:181], v[202:205], v[42:45]
	v_mfma_f32_16x16x32_bf16 v[38:41], v[186:189], v[194:197], v[38:41]
	v_mfma_f32_16x16x32_bf16 v[34:37], v[186:189], v[202:205], v[34:37]
	s_setprio 0
	s_barrier
	ds_read_b128 v[158:161], v136 offset:16384
	ds_read_b128 v[162:165], v136 offset:17408
	ds_read_b128 v[166:169], v136 offset:18432
	ds_read_b128 v[170:173], v136 offset:19456
	ds_read_b128 v[174:177], v136 offset:20480
	ds_read_b128 v[178:181], v136 offset:21504
	ds_read_b128 v[182:185], v136 offset:22528
	ds_read_b128 v[186:189], v136 offset:23552
	s_waitcnt vmcnt(4)
	s_barrier
	s_waitcnt lgkmcnt(0)
	s_setprio 3
	s_waitcnt lgkmcnt(0)
	v_mfma_f32_16x16x32_bf16 v[94:97], v[158:161], v[142:145], v[94:97]
	v_mfma_f32_16x16x32_bf16 v[90:93], v[158:161], v[150:153], v[90:93]
	v_mfma_f32_16x16x32_bf16 v[86:89], v[166:169], v[142:145], v[86:89]
	v_mfma_f32_16x16x32_bf16 v[82:85], v[166:169], v[150:153], v[82:85]
	v_mfma_f32_16x16x32_bf16 v[78:81], v[174:177], v[142:145], v[78:81]
	v_mfma_f32_16x16x32_bf16 v[74:77], v[174:177], v[150:153], v[74:77]
	v_mfma_f32_16x16x32_bf16 v[70:73], v[182:185], v[142:145], v[70:73]
	v_mfma_f32_16x16x32_bf16 v[66:69], v[182:185], v[150:153], v[66:69]
	v_mfma_f32_16x16x32_bf16 v[216:219], v[162:165], v[146:149], v[94:97]
	v_mfma_f32_16x16x32_bf16 v[220:223], v[162:165], v[154:157], v[90:93]
	v_mfma_f32_16x16x32_bf16 v[224:227], v[170:173], v[146:149], v[86:89]
	v_mfma_f32_16x16x32_bf16 v[228:231], v[170:173], v[154:157], v[82:85]
	v_mfma_f32_16x16x32_bf16 v[232:235], v[178:181], v[146:149], v[78:81]
	v_mfma_f32_16x16x32_bf16 v[236:239], v[178:181], v[154:157], v[74:77]
	v_mfma_f32_16x16x32_bf16 v[142:145], v[186:189], v[146:149], v[70:73]
	v_mfma_f32_16x16x32_bf16 v[146:149], v[186:189], v[154:157], v[66:69]
	s_setprio 0
	s_setprio 3
	v_mfma_f32_16x16x32_bf16 v[66:69], v[158:161], v[190:193], v[126:129]
	v_mfma_f32_16x16x32_bf16 v[150:153], v[162:165], v[194:197], v[66:69]
	v_mfma_f32_16x16x32_bf16 v[66:69], v[158:161], v[198:201], v[122:125]
	v_mfma_f32_16x16x32_bf16 v[154:157], v[162:165], v[202:205], v[66:69]
	v_mfma_f32_16x16x32_bf16 v[66:69], v[166:169], v[190:193], v[118:121]
	v_mfma_f32_16x16x32_bf16 v[158:161], v[170:173], v[194:197], v[66:69]
	v_mfma_f32_16x16x32_bf16 v[66:69], v[166:169], v[198:201], v[114:117]
	v_mfma_f32_16x16x32_bf16 v[162:165], v[170:173], v[202:205], v[66:69]
	v_mfma_f32_16x16x32_bf16 v[66:69], v[174:177], v[190:193], v[110:113]
	v_mfma_f32_16x16x32_bf16 v[166:169], v[178:181], v[194:197], v[66:69]
	v_mfma_f32_16x16x32_bf16 v[66:69], v[174:177], v[198:201], v[106:109]
	v_mfma_f32_16x16x32_bf16 v[170:173], v[178:181], v[202:205], v[66:69]
	v_mfma_f32_16x16x32_bf16 v[66:69], v[182:185], v[190:193], v[102:105]
	v_mfma_f32_16x16x32_bf16 v[174:177], v[186:189], v[194:197], v[66:69]
	v_mfma_f32_16x16x32_bf16 v[66:69], v[182:185], v[198:201], v[98:101]
	v_mfma_f32_16x16x32_bf16 v[178:181], v[186:189], v[202:205], v[66:69]
	s_setprio 0
	s_barrier
	ds_read_b128 v[182:185], v137 offset:32768
	ds_read_b128 v[186:189], v137 offset:33792
	ds_read_b128 v[190:193], v137 offset:34816
	ds_read_b128 v[194:197], v137 offset:35840
	ds_read_b128 v[74:77], v136 offset:32768
	ds_read_b128 v[78:81], v136 offset:33792
	ds_read_b128 v[90:93], v136 offset:34816
	ds_read_b128 v[94:97], v136 offset:35840
	ds_read_b128 v[198:201], v136 offset:36864
	ds_read_b128 v[202:205], v136 offset:37888
	ds_read_b128 v[240:243], v136 offset:38912
	ds_read_b128 v[244:247], v136 offset:39936
	s_waitcnt vmcnt(2)
	s_barrier
	s_waitcnt lgkmcnt(0)
	s_setprio 3
	s_waitcnt lgkmcnt(0)
	v_mfma_f32_16x16x32_bf16 v[30:33], v[74:77], v[182:185], v[30:33]
	v_mfma_f32_16x16x32_bf16 v[26:29], v[74:77], v[190:193], v[26:29]
	v_mfma_f32_16x16x32_bf16 v[22:25], v[90:93], v[182:185], v[22:25]
	v_mfma_f32_16x16x32_bf16 v[18:21], v[90:93], v[190:193], v[18:21]
	v_mfma_f32_16x16x32_bf16 v[14:17], v[198:201], v[182:185], v[14:17]
	v_mfma_f32_16x16x32_bf16 v[10:13], v[198:201], v[190:193], v[10:13]
	v_mfma_f32_16x16x32_bf16 v[6:9], v[240:243], v[182:185], v[6:9]
	v_mfma_f32_16x16x32_bf16 v[2:5], v[240:243], v[190:193], v[2:5]
	v_mfma_f32_16x16x32_bf16 v[118:121], v[78:81], v[186:189], v[30:33]
	v_mfma_f32_16x16x32_bf16 v[114:117], v[78:81], v[194:197], v[26:29]
	v_mfma_f32_16x16x32_bf16 v[102:105], v[94:97], v[186:189], v[22:25]
	v_mfma_f32_16x16x32_bf16 v[98:101], v[94:97], v[194:197], v[18:21]
	v_mfma_f32_16x16x32_bf16 v[86:89], v[202:205], v[186:189], v[14:17]
	v_mfma_f32_16x16x32_bf16 v[82:85], v[202:205], v[194:197], v[10:13]
	v_mfma_f32_16x16x32_bf16 v[70:73], v[244:247], v[186:189], v[6:9]
	v_mfma_f32_16x16x32_bf16 v[66:69], v[244:247], v[194:197], v[2:5]
	s_setprio 0
	s_barrier
	ds_read_b128 v[10:13], v137 offset:49152
	ds_read_b128 v[14:17], v137 offset:50176
	ds_read_b128 v[248:251], v137 offset:51200
	ds_read_b128 v[138:141], v137 offset:52224
	s_waitcnt vmcnt(0)
	s_barrier
	s_waitcnt lgkmcnt(0)
	s_setprio 3
	s_waitcnt lgkmcnt(0)
	v_mfma_f32_16x16x32_bf16 v[2:5], v[74:77], v[10:13], v[62:65]
	v_mfma_f32_16x16x32_bf16 v[126:129], v[78:81], v[14:17], v[2:5]
	v_mfma_f32_16x16x32_bf16 v[2:5], v[74:77], v[248:251], v[58:61]
	v_mfma_f32_16x16x32_bf16 v[122:125], v[78:81], v[138:141], v[2:5]
	v_mfma_f32_16x16x32_bf16 v[2:5], v[90:93], v[10:13], v[54:57]
	v_mfma_f32_16x16x32_bf16 v[110:113], v[94:97], v[14:17], v[2:5]
	v_mfma_f32_16x16x32_bf16 v[2:5], v[90:93], v[248:251], v[50:53]
	v_mfma_f32_16x16x32_bf16 v[106:109], v[94:97], v[138:141], v[2:5]
	v_mfma_f32_16x16x32_bf16 v[2:5], v[198:201], v[10:13], v[46:49]
	v_mfma_f32_16x16x32_bf16 v[94:97], v[202:205], v[14:17], v[2:5]
	v_mfma_f32_16x16x32_bf16 v[2:5], v[198:201], v[248:251], v[42:45]
	v_mfma_f32_16x16x32_bf16 v[90:93], v[202:205], v[138:141], v[2:5]
	v_mfma_f32_16x16x32_bf16 v[2:5], v[240:243], v[10:13], v[38:41]
	v_mfma_f32_16x16x32_bf16 v[78:81], v[244:247], v[14:17], v[2:5]
	v_mfma_f32_16x16x32_bf16 v[2:5], v[240:243], v[248:251], v[34:37]
	v_mfma_f32_16x16x32_bf16 v[74:77], v[244:247], v[138:141], v[2:5]
	s_setprio 0
	s_barrier
	ds_read_b128 v[26:29], v136 offset:49152
	ds_read_b128 v[30:33], v136 offset:50176
	ds_read_b128 v[42:45], v136 offset:51200
	ds_read_b128 v[198:201], v136 offset:52224
	ds_read_b128 v[202:205], v136 offset:53248
	ds_read_b128 v[240:243], v136 offset:54272
	ds_read_b128 v[244:247], v136 offset:55296
	ds_read_b128 v[212:215], v136 offset:56320
	s_barrier
	s_waitcnt lgkmcnt(0)
	s_setprio 3
	s_waitcnt lgkmcnt(0)
	v_mfma_f32_16x16x32_bf16 v[2:5], v[26:29], v[182:185], v[216:219]
	v_mfma_f32_16x16x32_bf16 v[54:57], v[30:33], v[186:189], v[2:5]
	v_mfma_f32_16x16x32_bf16 v[2:5], v[26:29], v[190:193], v[220:223]
	v_mfma_f32_16x16x32_bf16 v[50:53], v[30:33], v[194:197], v[2:5]
	v_mfma_f32_16x16x32_bf16 v[2:5], v[42:45], v[182:185], v[224:227]
	v_mfma_f32_16x16x32_bf16 v[38:41], v[198:201], v[186:189], v[2:5]
	v_mfma_f32_16x16x32_bf16 v[2:5], v[42:45], v[190:193], v[228:231]
	v_mfma_f32_16x16x32_bf16 v[34:37], v[198:201], v[194:197], v[2:5]
	v_mfma_f32_16x16x32_bf16 v[2:5], v[202:205], v[182:185], v[232:235]
	v_mfma_f32_16x16x32_bf16 v[22:25], v[240:243], v[186:189], v[2:5]
	v_mfma_f32_16x16x32_bf16 v[2:5], v[202:205], v[190:193], v[236:239]
	v_mfma_f32_16x16x32_bf16 v[18:21], v[240:243], v[194:197], v[2:5]
	v_mfma_f32_16x16x32_bf16 v[2:5], v[244:247], v[182:185], v[142:145]
	v_mfma_f32_16x16x32_bf16 v[6:9], v[212:215], v[186:189], v[2:5]
	v_mfma_f32_16x16x32_bf16 v[2:5], v[244:247], v[190:193], v[146:149]
	v_mfma_f32_16x16x32_bf16 v[2:5], v[212:215], v[194:197], v[2:5]
	s_setprio 0
	s_setprio 3
	v_mfma_f32_16x16x32_bf16 v[46:49], v[26:29], v[10:13], v[150:153]
	v_mfma_f32_16x16x32_bf16 v[26:29], v[26:29], v[248:251], v[154:157]
	v_mfma_f32_16x16x32_bf16 v[58:61], v[30:33], v[138:141], v[26:29]
	v_mfma_f32_16x16x32_bf16 v[26:29], v[42:45], v[10:13], v[158:161]
	v_mfma_f32_16x16x32_bf16 v[62:65], v[30:33], v[14:17], v[46:49]
	v_mfma_f32_16x16x32_bf16 v[46:49], v[198:201], v[14:17], v[26:29]
	v_mfma_f32_16x16x32_bf16 v[26:29], v[42:45], v[248:251], v[162:165]
	v_mfma_f32_16x16x32_bf16 v[42:45], v[198:201], v[138:141], v[26:29]
	v_mfma_f32_16x16x32_bf16 v[26:29], v[202:205], v[10:13], v[166:169]
	v_mfma_f32_16x16x32_bf16 v[10:13], v[244:247], v[10:13], v[174:177]
	v_mfma_f32_16x16x32_bf16 v[30:33], v[240:243], v[14:17], v[26:29]
	v_mfma_f32_16x16x32_bf16 v[26:29], v[202:205], v[248:251], v[170:173]
	v_mfma_f32_16x16x32_bf16 v[14:17], v[212:215], v[14:17], v[10:13]
	v_mfma_f32_16x16x32_bf16 v[10:13], v[244:247], v[248:251], v[178:181]
	v_mfma_f32_16x16x32_bf16 v[26:29], v[240:243], v[138:141], v[26:29]
	v_mfma_f32_16x16x32_bf16 v[10:13], v[212:215], v[138:141], v[10:13]
	s_setprio 0
	s_and_b64 vcc, exec, s[10:11]
	s_barrier
	s_cbranch_vccz .LBB0_471
	s_barrier
